# K-loop load segments: M0-hazard s_nop pads replaced by ds_read_b128 moved from the read burst (10 fewer issue slots per K-iteration)
# speedup vs baseline: 1.0066x; 1.0066x over previous
.LBB0_271:
	s_ashr_i32 s63, s62, 31
	s_lshl_b64 s[0:1], s[62:63], 20
	s_add_u32 s66, s49, s0
	s_addc_u32 s67, s82, s1
	s_and_b64 s[0:1], s[4:5], exec
	s_cselect_b32 s0, s67, s75
	s_cselect_b32 s1, s66, s74
	s_ashr_i32 s65, s64, 31
	s_lshl_b64 s[68:69], s[64:65], 20
	s_add_u32 s68, s45, s68
	s_addc_u32 s69, s47, s69
	s_and_b64 s[78:79], s[4:5], exec
	s_cselect_b32 s3, s69, s77
	s_cselect_b32 s63, s68, s76
	s_add_u32 s74, s74, 0x80080
	s_addc_u32 s75, s75, 0
	s_add_u32 s65, s76, 0x100
	s_addc_u32 s71, s77, 0
	s_mov_b32 s90, -2
	s_waitcnt vmcnt(0)
	ds_read_b128 v[146:149], v166
	ds_read_b128 v[150:153], v166 offset:1024
	ds_read_b128 v[154:157], v166 offset:2048
	ds_read_b128 v[170:173], v166 offset:3072
	ds_read_b128 v[174:177], v167
	ds_read_b128 v[178:181], v167 offset:1024
	ds_read_b128 v[182:185], v167 offset:2048
	ds_read_b128 v[186:189], v167 offset:3072
	s_add_u32 s76, s74, 0xfff80080
	s_addc_u32 s77, s75, -1
	s_cmp_eq_u32 s90, 28
	s_cselect_b32 s79, s0, s77
	s_cselect_b32 s78, s1, s76
	s_cselect_b32 s77, s3, s71
	s_cselect_b32 s76, s63, s65
	s_add_i32 m0, s31, 0xc000
	ds_read_b128 v[190:193], v168
	ds_read_b128 v[194:197], v168 offset:1024
	ds_read_b128 v[198:201], v168 offset:2048
	ds_read_b128 v[202:205], v168 offset:3072
	ds_read_b128 v[206:209], v168 offset:4096
	ds_read_b128 v[214:217], v168 offset:5120
	ds_read_b128 v[218:221], v168 offset:6144
	global_load_lds_dwordx4 v138, s[74:75]
	s_add_i32 m0, s31, 0xe000
	ds_read_b128 v[222:225], v168 offset:7168
	global_load_lds_dwordx4 v140, s[74:75]
	s_waitcnt vmcnt(8)
	s_waitcnt lgkmcnt(0)
	s_setprio 1
	s_barrier
	v_mfma_f32_16x16x32_bf16 v[124:127], v[146:149], v[190:193], 0
	v_mfma_f32_16x16x32_bf16 v[120:123], v[154:157], v[190:193], 0
	v_mfma_f32_16x16x32_bf16 v[108:111], v[146:149], v[198:201], 0
	v_mfma_f32_16x16x32_bf16 v[104:107], v[154:157], v[198:201], 0
	v_mfma_f32_16x16x32_bf16 v[92:95], v[146:149], v[206:209], 0
	v_mfma_f32_16x16x32_bf16 v[88:91], v[154:157], v[206:209], 0
	v_mfma_f32_16x16x32_bf16 v[76:79], v[146:149], v[218:221], 0
	v_mfma_f32_16x16x32_bf16 v[72:75], v[154:157], v[218:221], 0
	v_mfma_f32_16x16x32_bf16 v[124:127], v[150:153], v[194:197], v[124:127]
	v_mfma_f32_16x16x32_bf16 v[120:123], v[170:173], v[194:197], v[120:123]
	v_mfma_f32_16x16x32_bf16 v[108:111], v[150:153], v[202:205], v[108:111]
	v_mfma_f32_16x16x32_bf16 v[104:107], v[170:173], v[202:205], v[104:107]
	v_mfma_f32_16x16x32_bf16 v[92:95], v[150:153], v[214:217], v[92:95]
	v_mfma_f32_16x16x32_bf16 v[88:91], v[170:173], v[214:217], v[88:91]
	v_mfma_f32_16x16x32_bf16 v[76:79], v[150:153], v[222:225], v[76:79]
	v_mfma_f32_16x16x32_bf16 v[72:75], v[170:173], v[222:225], v[72:75]
	s_setprio 0
	s_setprio 1
	v_mfma_f32_16x16x32_bf16 v[116:119], v[174:177], v[190:193], 0
	v_mfma_f32_16x16x32_bf16 v[112:115], v[182:185], v[190:193], 0
	v_mfma_f32_16x16x32_bf16 v[100:103], v[174:177], v[198:201], 0
	v_mfma_f32_16x16x32_bf16 v[96:99], v[182:185], v[198:201], 0
	v_mfma_f32_16x16x32_bf16 v[84:87], v[174:177], v[206:209], 0
	v_mfma_f32_16x16x32_bf16 v[80:83], v[182:185], v[206:209], 0
	v_mfma_f32_16x16x32_bf16 v[68:71], v[174:177], v[218:221], 0
	v_mfma_f32_16x16x32_bf16 v[64:67], v[182:185], v[218:221], 0
	v_mfma_f32_16x16x32_bf16 v[116:119], v[178:181], v[194:197], v[116:119]
	v_mfma_f32_16x16x32_bf16 v[112:115], v[186:189], v[194:197], v[112:115]
	v_mfma_f32_16x16x32_bf16 v[100:103], v[178:181], v[202:205], v[100:103]
	v_mfma_f32_16x16x32_bf16 v[96:99], v[186:189], v[202:205], v[96:99]
	v_mfma_f32_16x16x32_bf16 v[84:87], v[178:181], v[214:217], v[84:87]
	v_mfma_f32_16x16x32_bf16 v[80:83], v[186:189], v[214:217], v[80:83]
	v_mfma_f32_16x16x32_bf16 v[68:71], v[178:181], v[222:225], v[68:71]
	v_mfma_f32_16x16x32_bf16 v[64:67], v[186:189], v[222:225], v[64:67]
	s_barrier
	s_setprio 0
	s_add_i32 s91, s81, s30
	s_add_u32 s98, s76, s34
	s_addc_u32 s99, s77, s35
	s_mov_b32 m0, s91
	ds_read_b128 v[190:193], v168 offset:16384
	ds_read_b128 v[194:197], v168 offset:17408
	ds_read_b128 v[198:201], v168 offset:18432
	ds_read_b128 v[202:205], v168 offset:19456
	ds_read_b128 v[206:209], v168 offset:20480
	global_load_lds_dwordx4 v130, s[76:77]
	s_add_i32 m0, s91, 0x2000
	s_add_u32 s92, s76, 0x80000
	s_addc_u32 s93, s77, 0
	s_add_i32 s91, s83, s30
	global_load_lds_dwordx4 v134, s[76:77]
	s_mov_b32 m0, s91
	s_add_u32 s100, s78, s34
	s_addc_u32 s101, s79, s35
	global_load_lds_dwordx4 v130, s[92:93]
	s_add_i32 m0, s91, 0x2000
	ds_read_b128 v[222:225], v168 offset:23552
	global_load_lds_dwordx4 v134, s[92:93]
	s_mov_b32 m0, s31
	ds_read_b128 v[218:221], v168 offset:22528
	global_load_lds_dwordx4 v128, s[78:79]
	s_mov_b32 m0, s51
	ds_read_b128 v[214:217], v168 offset:21504
	global_load_lds_dwordx4 v132, s[78:79]
	s_waitcnt vmcnt(8)
	s_waitcnt lgkmcnt(0)
	s_setprio 1
	s_barrier
	v_mfma_f32_16x16x32_bf16 v[60:63], v[146:149], v[190:193], 0
	v_mfma_f32_16x16x32_bf16 v[56:59], v[154:157], v[190:193], 0
	v_mfma_f32_16x16x32_bf16 v[44:47], v[146:149], v[198:201], 0
	v_mfma_f32_16x16x32_bf16 v[40:43], v[154:157], v[198:201], 0
	v_mfma_f32_16x16x32_bf16 v[28:31], v[146:149], v[206:209], 0
	v_mfma_f32_16x16x32_bf16 v[24:27], v[154:157], v[206:209], 0
	v_mfma_f32_16x16x32_bf16 v[12:15], v[146:149], v[218:221], 0
	v_mfma_f32_16x16x32_bf16 v[8:11], v[154:157], v[218:221], 0
	v_mfma_f32_16x16x32_bf16 v[60:63], v[150:153], v[194:197], v[60:63]
	v_mfma_f32_16x16x32_bf16 v[56:59], v[170:173], v[194:197], v[56:59]
	v_mfma_f32_16x16x32_bf16 v[44:47], v[150:153], v[202:205], v[44:47]
	v_mfma_f32_16x16x32_bf16 v[40:43], v[170:173], v[202:205], v[40:43]
	v_mfma_f32_16x16x32_bf16 v[28:31], v[150:153], v[214:217], v[28:31]
	v_mfma_f32_16x16x32_bf16 v[24:27], v[170:173], v[214:217], v[24:27]
	v_mfma_f32_16x16x32_bf16 v[12:15], v[150:153], v[222:225], v[12:15]
	v_mfma_f32_16x16x32_bf16 v[8:11], v[170:173], v[222:225], v[8:11]
	s_setprio 0
	s_setprio 1
	v_mfma_f32_16x16x32_bf16 v[52:55], v[174:177], v[190:193], 0
	v_mfma_f32_16x16x32_bf16 v[48:51], v[182:185], v[190:193], 0
	v_mfma_f32_16x16x32_bf16 v[36:39], v[174:177], v[198:201], 0
	v_mfma_f32_16x16x32_bf16 v[32:35], v[182:185], v[198:201], 0
	v_mfma_f32_16x16x32_bf16 v[20:23], v[174:177], v[206:209], 0
	v_mfma_f32_16x16x32_bf16 v[16:19], v[182:185], v[206:209], 0
	v_mfma_f32_16x16x32_bf16 v[4:7], v[174:177], v[218:221], 0
	v_mfma_f32_16x16x32_bf16 v[0:3], v[182:185], v[218:221], 0
	v_mfma_f32_16x16x32_bf16 v[52:55], v[178:181], v[194:197], v[52:55]
	v_mfma_f32_16x16x32_bf16 v[48:51], v[186:189], v[194:197], v[48:51]
	v_mfma_f32_16x16x32_bf16 v[36:39], v[178:181], v[202:205], v[36:39]
	v_mfma_f32_16x16x32_bf16 v[32:35], v[186:189], v[202:205], v[32:35]
	v_mfma_f32_16x16x32_bf16 v[20:23], v[178:181], v[214:217], v[20:23]
	v_mfma_f32_16x16x32_bf16 v[16:19], v[186:189], v[214:217], v[16:19]
	v_mfma_f32_16x16x32_bf16 v[4:7], v[178:181], v[222:225], v[4:7]
	v_mfma_f32_16x16x32_bf16 v[0:3], v[186:189], v[222:225], v[0:3]
	s_barrier
	s_setprio 0
	s_add_i32 s91, 0, 0x18000
	v_add_u32_e32 v136, s91, v162
	s_add_i32 s92, 0, 0x1c000
	ds_read_b128 v[146:149], v136
	ds_read_b128 v[150:153], v136 offset:1024
	ds_read_b128 v[154:157], v136 offset:2048
	ds_read_b128 v[170:173], v136 offset:3072
	v_add_u32_e32 v136, s92, v162
	ds_read_b128 v[174:177], v136
	ds_read_b128 v[178:181], v136 offset:1024
	ds_read_b128 v[182:185], v136 offset:2048
	ds_read_b128 v[186:189], v136 offset:3072
	s_add_u32 s78, s78, 0x80000
	s_addc_u32 s79, s79, 0
	s_mov_b32 m0, s28
	ds_read_b128 v[190:193], v168 offset:32768
	ds_read_b128 v[194:197], v168 offset:33792
	ds_read_b128 v[198:201], v168 offset:34816
	ds_read_b128 v[202:205], v168 offset:35840
	ds_read_b128 v[206:209], v168 offset:36864
	ds_read_b128 v[214:217], v168 offset:37888
	ds_read_b128 v[218:221], v168 offset:38912
	global_load_lds_dwordx4 v128, s[78:79]
	s_mov_b32 m0, s29
	ds_read_b128 v[222:225], v168 offset:39936
	global_load_lds_dwordx4 v132, s[78:79]
	s_waitcnt vmcnt(8)
	s_waitcnt lgkmcnt(0)
	s_setprio 1
	s_barrier
	v_mfma_f32_16x16x32_bf16 v[124:127], v[146:149], v[190:193], v[124:127]
	v_mfma_f32_16x16x32_bf16 v[120:123], v[154:157], v[190:193], v[120:123]
	v_mfma_f32_16x16x32_bf16 v[108:111], v[146:149], v[198:201], v[108:111]
	v_mfma_f32_16x16x32_bf16 v[104:107], v[154:157], v[198:201], v[104:107]
	v_mfma_f32_16x16x32_bf16 v[92:95], v[146:149], v[206:209], v[92:95]
	v_mfma_f32_16x16x32_bf16 v[88:91], v[154:157], v[206:209], v[88:91]
	v_mfma_f32_16x16x32_bf16 v[76:79], v[146:149], v[218:221], v[76:79]
	v_mfma_f32_16x16x32_bf16 v[72:75], v[154:157], v[218:221], v[72:75]
	v_mfma_f32_16x16x32_bf16 v[124:127], v[150:153], v[194:197], v[124:127]
	v_mfma_f32_16x16x32_bf16 v[120:123], v[170:173], v[194:197], v[120:123]
	v_mfma_f32_16x16x32_bf16 v[108:111], v[150:153], v[202:205], v[108:111]
	v_mfma_f32_16x16x32_bf16 v[104:107], v[170:173], v[202:205], v[104:107]
	v_mfma_f32_16x16x32_bf16 v[92:95], v[150:153], v[214:217], v[92:95]
	v_mfma_f32_16x16x32_bf16 v[88:91], v[170:173], v[214:217], v[88:91]
	v_mfma_f32_16x16x32_bf16 v[76:79], v[150:153], v[222:225], v[76:79]
	v_mfma_f32_16x16x32_bf16 v[72:75], v[170:173], v[222:225], v[72:75]
	s_setprio 0
	s_setprio 1
	v_mfma_f32_16x16x32_bf16 v[116:119], v[174:177], v[190:193], v[116:119]
	v_mfma_f32_16x16x32_bf16 v[112:115], v[182:185], v[190:193], v[112:115]
	v_mfma_f32_16x16x32_bf16 v[100:103], v[174:177], v[198:201], v[100:103]
	v_mfma_f32_16x16x32_bf16 v[96:99], v[182:185], v[198:201], v[96:99]
	v_mfma_f32_16x16x32_bf16 v[84:87], v[174:177], v[206:209], v[84:87]
	v_mfma_f32_16x16x32_bf16 v[80:83], v[182:185], v[206:209], v[80:83]
	v_mfma_f32_16x16x32_bf16 v[68:71], v[174:177], v[218:221], v[68:71]
	v_mfma_f32_16x16x32_bf16 v[64:67], v[182:185], v[218:221], v[64:67]
	v_mfma_f32_16x16x32_bf16 v[116:119], v[178:181], v[194:197], v[116:119]
	v_mfma_f32_16x16x32_bf16 v[112:115], v[186:189], v[194:197], v[112:115]
	v_mfma_f32_16x16x32_bf16 v[100:103], v[178:181], v[202:205], v[100:103]
	v_mfma_f32_16x16x32_bf16 v[96:99], v[186:189], v[202:205], v[96:99]
	v_mfma_f32_16x16x32_bf16 v[84:87], v[178:181], v[214:217], v[84:87]
	v_mfma_f32_16x16x32_bf16 v[80:83], v[186:189], v[214:217], v[80:83]
	v_mfma_f32_16x16x32_bf16 v[68:71], v[178:181], v[222:225], v[68:71]
	v_mfma_f32_16x16x32_bf16 v[64:67], v[186:189], v[222:225], v[64:67]
	s_barrier
	s_setprio 0
	s_add_i32 s78, s91, s30
	s_mov_b32 m0, s78
	ds_read_b128 v[190:193], v168 offset:49152
	ds_read_b128 v[194:197], v168 offset:50176
	ds_read_b128 v[198:201], v168 offset:51200
	ds_read_b128 v[202:205], v168 offset:52224
	global_load_lds_dwordx4 v130, s[98:99]
	s_add_i32 m0, s78, 0x2000
	s_add_u32 s76, s76, 0x80080
	s_addc_u32 s77, s77, 0
	s_add_i32 s78, s92, s30
	global_load_lds_dwordx4 v134, s[98:99]
	s_mov_b32 m0, s78
	ds_read_b128 v[222:225], v168 offset:56320
	global_load_lds_dwordx4 v130, s[76:77]
	s_add_i32 m0, s78, 0x2000
	ds_read_b128 v[218:221], v168 offset:55296
	global_load_lds_dwordx4 v134, s[76:77]
	s_mov_b32 m0, s73
	ds_read_b128 v[214:217], v168 offset:54272
	global_load_lds_dwordx4 v128, s[100:101]
	s_mov_b32 m0, s80
	ds_read_b128 v[206:209], v168 offset:53248
	global_load_lds_dwordx4 v132, s[100:101]
	s_waitcnt vmcnt(8)
	s_waitcnt lgkmcnt(0)
	s_setprio 1
	s_barrier
	v_mfma_f32_16x16x32_bf16 v[60:63], v[146:149], v[190:193], v[60:63]
	v_mfma_f32_16x16x32_bf16 v[56:59], v[154:157], v[190:193], v[56:59]
	v_mfma_f32_16x16x32_bf16 v[44:47], v[146:149], v[198:201], v[44:47]
	v_mfma_f32_16x16x32_bf16 v[40:43], v[154:157], v[198:201], v[40:43]
	v_mfma_f32_16x16x32_bf16 v[28:31], v[146:149], v[206:209], v[28:31]
	v_mfma_f32_16x16x32_bf16 v[24:27], v[154:157], v[206:209], v[24:27]
	v_mfma_f32_16x16x32_bf16 v[12:15], v[146:149], v[218:221], v[12:15]
	v_mfma_f32_16x16x32_bf16 v[8:11], v[154:157], v[218:221], v[8:11]
	v_mfma_f32_16x16x32_bf16 v[60:63], v[150:153], v[194:197], v[60:63]
	v_mfma_f32_16x16x32_bf16 v[56:59], v[170:173], v[194:197], v[56:59]
	v_mfma_f32_16x16x32_bf16 v[44:47], v[150:153], v[202:205], v[44:47]
	v_mfma_f32_16x16x32_bf16 v[40:43], v[170:173], v[202:205], v[40:43]
	v_mfma_f32_16x16x32_bf16 v[28:31], v[150:153], v[214:217], v[28:31]
	v_mfma_f32_16x16x32_bf16 v[24:27], v[170:173], v[214:217], v[24:27]
	v_mfma_f32_16x16x32_bf16 v[12:15], v[150:153], v[222:225], v[12:15]
	v_mfma_f32_16x16x32_bf16 v[8:11], v[170:173], v[222:225], v[8:11]
	s_setprio 0
	s_setprio 1
	v_mfma_f32_16x16x32_bf16 v[52:55], v[174:177], v[190:193], v[52:55]
	v_mfma_f32_16x16x32_bf16 v[48:51], v[182:185], v[190:193], v[48:51]
	v_mfma_f32_16x16x32_bf16 v[36:39], v[174:177], v[198:201], v[36:39]
	v_mfma_f32_16x16x32_bf16 v[32:35], v[182:185], v[198:201], v[32:35]
	v_mfma_f32_16x16x32_bf16 v[20:23], v[174:177], v[206:209], v[20:23]
	v_mfma_f32_16x16x32_bf16 v[16:19], v[182:185], v[206:209], v[16:19]
	v_mfma_f32_16x16x32_bf16 v[4:7], v[174:177], v[218:221], v[4:7]
	v_mfma_f32_16x16x32_bf16 v[0:3], v[182:185], v[218:221], v[0:3]
	v_mfma_f32_16x16x32_bf16 v[52:55], v[178:181], v[194:197], v[52:55]
	v_mfma_f32_16x16x32_bf16 v[48:51], v[186:189], v[194:197], v[48:51]
	v_mfma_f32_16x16x32_bf16 v[36:39], v[178:181], v[202:205], v[36:39]
	v_mfma_f32_16x16x32_bf16 v[32:35], v[186:189], v[202:205], v[32:35]
	v_mfma_f32_16x16x32_bf16 v[20:23], v[178:181], v[214:217], v[20:23]
	v_mfma_f32_16x16x32_bf16 v[16:19], v[186:189], v[214:217], v[16:19]
	v_mfma_f32_16x16x32_bf16 v[4:7], v[178:181], v[222:225], v[4:7]
	v_mfma_f32_16x16x32_bf16 v[0:3], v[186:189], v[222:225], v[0:3]
	s_barrier
	s_setprio 0
	s_add_i32 s90, s90, 2
	s_add_u32 s74, s74, 0x100
	s_addc_u32 s75, s75, 0
	s_add_u32 s65, s65, 0x100
	s_addc_u32 s71, s71, 0
	s_cmp_gt_u32 s90, 29
.LBB0_272:
	ds_read_b128 v[146:149], v166
	ds_read_b128 v[150:153], v166 offset:1024
	ds_read_b128 v[154:157], v166 offset:2048
	ds_read_b128 v[170:173], v166 offset:3072
	ds_read_b128 v[174:177], v167
	ds_read_b128 v[178:181], v167 offset:1024
	ds_read_b128 v[182:185], v167 offset:2048
	ds_read_b128 v[186:189], v167 offset:3072
	s_add_u32 s76, s74, 0xfff80080
	s_addc_u32 s77, s75, -1
	s_cmp_eq_u32 s90, 28
	s_cselect_b32 s79, s0, s77
	s_cselect_b32 s78, s1, s76
	s_cselect_b32 s77, s3, s71
	s_cselect_b32 s76, s63, s65
	s_add_i32 m0, s31, 0xc000
	ds_read_b128 v[190:193], v168
	ds_read_b128 v[194:197], v168 offset:1024
	ds_read_b128 v[198:201], v168 offset:2048
	ds_read_b128 v[202:205], v168 offset:3072
	ds_read_b128 v[206:209], v168 offset:4096
	ds_read_b128 v[214:217], v168 offset:5120
	ds_read_b128 v[218:221], v168 offset:6144
	global_load_lds_dwordx4 v138, s[74:75]
	s_add_i32 m0, s31, 0xe000
	ds_read_b128 v[222:225], v168 offset:7168
	global_load_lds_dwordx4 v140, s[74:75]
	s_waitcnt vmcnt(8)
	s_waitcnt lgkmcnt(0)
	s_setprio 1
	s_barrier
	v_mfma_f32_16x16x32_bf16 v[124:127], v[146:149], v[190:193], v[124:127]
	v_mfma_f32_16x16x32_bf16 v[120:123], v[154:157], v[190:193], v[120:123]
	v_mfma_f32_16x16x32_bf16 v[108:111], v[146:149], v[198:201], v[108:111]
	v_mfma_f32_16x16x32_bf16 v[104:107], v[154:157], v[198:201], v[104:107]
	v_mfma_f32_16x16x32_bf16 v[92:95], v[146:149], v[206:209], v[92:95]
	v_mfma_f32_16x16x32_bf16 v[88:91], v[154:157], v[206:209], v[88:91]
	v_mfma_f32_16x16x32_bf16 v[76:79], v[146:149], v[218:221], v[76:79]
	v_mfma_f32_16x16x32_bf16 v[72:75], v[154:157], v[218:221], v[72:75]
	v_mfma_f32_16x16x32_bf16 v[124:127], v[150:153], v[194:197], v[124:127]
	v_mfma_f32_16x16x32_bf16 v[120:123], v[170:173], v[194:197], v[120:123]
	v_mfma_f32_16x16x32_bf16 v[108:111], v[150:153], v[202:205], v[108:111]
	v_mfma_f32_16x16x32_bf16 v[104:107], v[170:173], v[202:205], v[104:107]
	v_mfma_f32_16x16x32_bf16 v[92:95], v[150:153], v[214:217], v[92:95]
	v_mfma_f32_16x16x32_bf16 v[88:91], v[170:173], v[214:217], v[88:91]
	v_mfma_f32_16x16x32_bf16 v[76:79], v[150:153], v[222:225], v[76:79]
	v_mfma_f32_16x16x32_bf16 v[72:75], v[170:173], v[222:225], v[72:75]
	s_setprio 0
	s_setprio 1
	v_mfma_f32_16x16x32_bf16 v[116:119], v[174:177], v[190:193], v[116:119]
	v_mfma_f32_16x16x32_bf16 v[112:115], v[182:185], v[190:193], v[112:115]
	v_mfma_f32_16x16x32_bf16 v[100:103], v[174:177], v[198:201], v[100:103]
	v_mfma_f32_16x16x32_bf16 v[96:99], v[182:185], v[198:201], v[96:99]
	v_mfma_f32_16x16x32_bf16 v[84:87], v[174:177], v[206:209], v[84:87]
	v_mfma_f32_16x16x32_bf16 v[80:83], v[182:185], v[206:209], v[80:83]
	v_mfma_f32_16x16x32_bf16 v[68:71], v[174:177], v[218:221], v[68:71]
	v_mfma_f32_16x16x32_bf16 v[64:67], v[182:185], v[218:221], v[64:67]
	v_mfma_f32_16x16x32_bf16 v[116:119], v[178:181], v[194:197], v[116:119]
	v_mfma_f32_16x16x32_bf16 v[112:115], v[186:189], v[194:197], v[112:115]
	v_mfma_f32_16x16x32_bf16 v[100:103], v[178:181], v[202:205], v[100:103]
	v_mfma_f32_16x16x32_bf16 v[96:99], v[186:189], v[202:205], v[96:99]
	v_mfma_f32_16x16x32_bf16 v[84:87], v[178:181], v[214:217], v[84:87]
	v_mfma_f32_16x16x32_bf16 v[80:83], v[186:189], v[214:217], v[80:83]
	v_mfma_f32_16x16x32_bf16 v[68:71], v[178:181], v[222:225], v[68:71]
	v_mfma_f32_16x16x32_bf16 v[64:67], v[186:189], v[222:225], v[64:67]
	s_barrier
	s_setprio 0
	s_add_i32 s91, s81, s30
	s_add_u32 s98, s76, s34
	s_addc_u32 s99, s77, s35
	s_mov_b32 m0, s91
	ds_read_b128 v[190:193], v168 offset:16384
	ds_read_b128 v[194:197], v168 offset:17408
	ds_read_b128 v[198:201], v168 offset:18432
	ds_read_b128 v[202:205], v168 offset:19456
	ds_read_b128 v[206:209], v168 offset:20480
	global_load_lds_dwordx4 v130, s[76:77]
	s_add_i32 m0, s91, 0x2000
	s_add_u32 s92, s76, 0x80000
	s_addc_u32 s93, s77, 0
	s_add_i32 s91, s83, s30
	global_load_lds_dwordx4 v134, s[76:77]
	s_mov_b32 m0, s91
	s_add_u32 s100, s78, s34
	s_addc_u32 s101, s79, s35
	global_load_lds_dwordx4 v130, s[92:93]
	s_add_i32 m0, s91, 0x2000
	ds_read_b128 v[222:225], v168 offset:23552
	global_load_lds_dwordx4 v134, s[92:93]
	s_mov_b32 m0, s31
	ds_read_b128 v[218:221], v168 offset:22528
	global_load_lds_dwordx4 v128, s[78:79]
	s_mov_b32 m0, s51
	ds_read_b128 v[214:217], v168 offset:21504
	global_load_lds_dwordx4 v132, s[78:79]
	s_waitcnt vmcnt(8)
	s_waitcnt lgkmcnt(0)
	s_setprio 1
	s_barrier
	v_mfma_f32_16x16x32_bf16 v[60:63], v[146:149], v[190:193], v[60:63]
	v_mfma_f32_16x16x32_bf16 v[56:59], v[154:157], v[190:193], v[56:59]
	v_mfma_f32_16x16x32_bf16 v[44:47], v[146:149], v[198:201], v[44:47]
	v_mfma_f32_16x16x32_bf16 v[40:43], v[154:157], v[198:201], v[40:43]
	v_mfma_f32_16x16x32_bf16 v[28:31], v[146:149], v[206:209], v[28:31]
	v_mfma_f32_16x16x32_bf16 v[24:27], v[154:157], v[206:209], v[24:27]
	v_mfma_f32_16x16x32_bf16 v[12:15], v[146:149], v[218:221], v[12:15]
	v_mfma_f32_16x16x32_bf16 v[8:11], v[154:157], v[218:221], v[8:11]
	v_mfma_f32_16x16x32_bf16 v[60:63], v[150:153], v[194:197], v[60:63]
	v_mfma_f32_16x16x32_bf16 v[56:59], v[170:173], v[194:197], v[56:59]
	v_mfma_f32_16x16x32_bf16 v[44:47], v[150:153], v[202:205], v[44:47]
	v_mfma_f32_16x16x32_bf16 v[40:43], v[170:173], v[202:205], v[40:43]
	v_mfma_f32_16x16x32_bf16 v[28:31], v[150:153], v[214:217], v[28:31]
	v_mfma_f32_16x16x32_bf16 v[24:27], v[170:173], v[214:217], v[24:27]
	v_mfma_f32_16x16x32_bf16 v[12:15], v[150:153], v[222:225], v[12:15]
	v_mfma_f32_16x16x32_bf16 v[8:11], v[170:173], v[222:225], v[8:11]
	s_setprio 0
	s_setprio 1
	v_mfma_f32_16x16x32_bf16 v[52:55], v[174:177], v[190:193], v[52:55]
	v_mfma_f32_16x16x32_bf16 v[48:51], v[182:185], v[190:193], v[48:51]
	v_mfma_f32_16x16x32_bf16 v[36:39], v[174:177], v[198:201], v[36:39]
	v_mfma_f32_16x16x32_bf16 v[32:35], v[182:185], v[198:201], v[32:35]
	v_mfma_f32_16x16x32_bf16 v[20:23], v[174:177], v[206:209], v[20:23]
	v_mfma_f32_16x16x32_bf16 v[16:19], v[182:185], v[206:209], v[16:19]
	v_mfma_f32_16x16x32_bf16 v[4:7], v[174:177], v[218:221], v[4:7]
	v_mfma_f32_16x16x32_bf16 v[0:3], v[182:185], v[218:221], v[0:3]
	v_mfma_f32_16x16x32_bf16 v[52:55], v[178:181], v[194:197], v[52:55]
	v_mfma_f32_16x16x32_bf16 v[48:51], v[186:189], v[194:197], v[48:51]
	v_mfma_f32_16x16x32_bf16 v[36:39], v[178:181], v[202:205], v[36:39]
	v_mfma_f32_16x16x32_bf16 v[32:35], v[186:189], v[202:205], v[32:35]
	v_mfma_f32_16x16x32_bf16 v[20:23], v[178:181], v[214:217], v[20:23]
	v_mfma_f32_16x16x32_bf16 v[16:19], v[186:189], v[214:217], v[16:19]
	v_mfma_f32_16x16x32_bf16 v[4:7], v[178:181], v[222:225], v[4:7]
	v_mfma_f32_16x16x32_bf16 v[0:3], v[186:189], v[222:225], v[0:3]
	s_barrier
	s_setprio 0
	s_add_i32 s91, 0, 0x18000
	v_add_u32_e32 v136, s91, v162
	s_add_i32 s92, 0, 0x1c000
	ds_read_b128 v[146:149], v136
	ds_read_b128 v[150:153], v136 offset:1024
	ds_read_b128 v[154:157], v136 offset:2048
	ds_read_b128 v[170:173], v136 offset:3072
	v_add_u32_e32 v136, s92, v162
	ds_read_b128 v[174:177], v136
	ds_read_b128 v[178:181], v136 offset:1024
	ds_read_b128 v[182:185], v136 offset:2048
	ds_read_b128 v[186:189], v136 offset:3072
	s_add_u32 s78, s78, 0x80000
	s_addc_u32 s79, s79, 0
	s_mov_b32 m0, s28
	ds_read_b128 v[190:193], v168 offset:32768
	ds_read_b128 v[194:197], v168 offset:33792
	ds_read_b128 v[198:201], v168 offset:34816
	ds_read_b128 v[202:205], v168 offset:35840
	ds_read_b128 v[206:209], v168 offset:36864
	ds_read_b128 v[214:217], v168 offset:37888
	ds_read_b128 v[218:221], v168 offset:38912
	global_load_lds_dwordx4 v128, s[78:79]
	s_mov_b32 m0, s29
	ds_read_b128 v[222:225], v168 offset:39936
	global_load_lds_dwordx4 v132, s[78:79]
	s_waitcnt vmcnt(8)
	s_waitcnt lgkmcnt(0)
	s_setprio 1
	s_barrier
	v_mfma_f32_16x16x32_bf16 v[124:127], v[146:149], v[190:193], v[124:127]
	v_mfma_f32_16x16x32_bf16 v[120:123], v[154:157], v[190:193], v[120:123]
	v_mfma_f32_16x16x32_bf16 v[108:111], v[146:149], v[198:201], v[108:111]
	v_mfma_f32_16x16x32_bf16 v[104:107], v[154:157], v[198:201], v[104:107]
	v_mfma_f32_16x16x32_bf16 v[92:95], v[146:149], v[206:209], v[92:95]
	v_mfma_f32_16x16x32_bf16 v[88:91], v[154:157], v[206:209], v[88:91]
	v_mfma_f32_16x16x32_bf16 v[76:79], v[146:149], v[218:221], v[76:79]
	v_mfma_f32_16x16x32_bf16 v[72:75], v[154:157], v[218:221], v[72:75]
	v_mfma_f32_16x16x32_bf16 v[124:127], v[150:153], v[194:197], v[124:127]
	v_mfma_f32_16x16x32_bf16 v[120:123], v[170:173], v[194:197], v[120:123]
	v_mfma_f32_16x16x32_bf16 v[108:111], v[150:153], v[202:205], v[108:111]
	v_mfma_f32_16x16x32_bf16 v[104:107], v[170:173], v[202:205], v[104:107]
	v_mfma_f32_16x16x32_bf16 v[92:95], v[150:153], v[214:217], v[92:95]
	v_mfma_f32_16x16x32_bf16 v[88:91], v[170:173], v[214:217], v[88:91]
	v_mfma_f32_16x16x32_bf16 v[76:79], v[150:153], v[222:225], v[76:79]
	v_mfma_f32_16x16x32_bf16 v[72:75], v[170:173], v[222:225], v[72:75]
	s_setprio 0
	s_setprio 1
	v_mfma_f32_16x16x32_bf16 v[116:119], v[174:177], v[190:193], v[116:119]
	v_mfma_f32_16x16x32_bf16 v[112:115], v[182:185], v[190:193], v[112:115]
	v_mfma_f32_16x16x32_bf16 v[100:103], v[174:177], v[198:201], v[100:103]
	v_mfma_f32_16x16x32_bf16 v[96:99], v[182:185], v[198:201], v[96:99]
	v_mfma_f32_16x16x32_bf16 v[84:87], v[174:177], v[206:209], v[84:87]
	v_mfma_f32_16x16x32_bf16 v[80:83], v[182:185], v[206:209], v[80:83]
	v_mfma_f32_16x16x32_bf16 v[68:71], v[174:177], v[218:221], v[68:71]
	v_mfma_f32_16x16x32_bf16 v[64:67], v[182:185], v[218:221], v[64:67]
	v_mfma_f32_16x16x32_bf16 v[116:119], v[178:181], v[194:197], v[116:119]
	v_mfma_f32_16x16x32_bf16 v[112:115], v[186:189], v[194:197], v[112:115]
	v_mfma_f32_16x16x32_bf16 v[100:103], v[178:181], v[202:205], v[100:103]
	v_mfma_f32_16x16x32_bf16 v[96:99], v[186:189], v[202:205], v[96:99]
	v_mfma_f32_16x16x32_bf16 v[84:87], v[178:181], v[214:217], v[84:87]
	v_mfma_f32_16x16x32_bf16 v[80:83], v[186:189], v[214:217], v[80:83]
	v_mfma_f32_16x16x32_bf16 v[68:71], v[178:181], v[222:225], v[68:71]
	v_mfma_f32_16x16x32_bf16 v[64:67], v[186:189], v[222:225], v[64:67]
	s_barrier
	s_setprio 0
	s_add_i32 s78, s91, s30
	s_mov_b32 m0, s78
	ds_read_b128 v[190:193], v168 offset:49152
	ds_read_b128 v[194:197], v168 offset:50176
	ds_read_b128 v[198:201], v168 offset:51200
	ds_read_b128 v[202:205], v168 offset:52224
	global_load_lds_dwordx4 v130, s[98:99]
	s_add_i32 m0, s78, 0x2000
	s_add_u32 s76, s76, 0x80080
	s_addc_u32 s77, s77, 0
	s_add_i32 s78, s92, s30
	global_load_lds_dwordx4 v134, s[98:99]
	s_mov_b32 m0, s78
	ds_read_b128 v[222:225], v168 offset:56320
	global_load_lds_dwordx4 v130, s[76:77]
	s_add_i32 m0, s78, 0x2000
	ds_read_b128 v[218:221], v168 offset:55296
	global_load_lds_dwordx4 v134, s[76:77]
	s_mov_b32 m0, s73
	ds_read_b128 v[214:217], v168 offset:54272
	global_load_lds_dwordx4 v128, s[100:101]
	s_mov_b32 m0, s80
	ds_read_b128 v[206:209], v168 offset:53248
	global_load_lds_dwordx4 v132, s[100:101]
	s_waitcnt vmcnt(8)
	s_waitcnt lgkmcnt(0)
	s_setprio 1
	s_barrier
	v_mfma_f32_16x16x32_bf16 v[60:63], v[146:149], v[190:193], v[60:63]
	v_mfma_f32_16x16x32_bf16 v[56:59], v[154:157], v[190:193], v[56:59]
	v_mfma_f32_16x16x32_bf16 v[44:47], v[146:149], v[198:201], v[44:47]
	v_mfma_f32_16x16x32_bf16 v[40:43], v[154:157], v[198:201], v[40:43]
	v_mfma_f32_16x16x32_bf16 v[28:31], v[146:149], v[206:209], v[28:31]
	v_mfma_f32_16x16x32_bf16 v[24:27], v[154:157], v[206:209], v[24:27]
	v_mfma_f32_16x16x32_bf16 v[12:15], v[146:149], v[218:221], v[12:15]
	v_mfma_f32_16x16x32_bf16 v[8:11], v[154:157], v[218:221], v[8:11]
	v_mfma_f32_16x16x32_bf16 v[60:63], v[150:153], v[194:197], v[60:63]
	v_mfma_f32_16x16x32_bf16 v[56:59], v[170:173], v[194:197], v[56:59]
	v_mfma_f32_16x16x32_bf16 v[44:47], v[150:153], v[202:205], v[44:47]
	v_mfma_f32_16x16x32_bf16 v[40:43], v[170:173], v[202:205], v[40:43]
	v_mfma_f32_16x16x32_bf16 v[28:31], v[150:153], v[214:217], v[28:31]
	v_mfma_f32_16x16x32_bf16 v[24:27], v[170:173], v[214:217], v[24:27]
	v_mfma_f32_16x16x32_bf16 v[12:15], v[150:153], v[222:225], v[12:15]
	v_mfma_f32_16x16x32_bf16 v[8:11], v[170:173], v[222:225], v[8:11]
	s_setprio 0
	s_setprio 1
	v_mfma_f32_16x16x32_bf16 v[52:55], v[174:177], v[190:193], v[52:55]
	v_mfma_f32_16x16x32_bf16 v[48:51], v[182:185], v[190:193], v[48:51]
	v_mfma_f32_16x16x32_bf16 v[36:39], v[174:177], v[198:201], v[36:39]
	v_mfma_f32_16x16x32_bf16 v[32:35], v[182:185], v[198:201], v[32:35]
	v_mfma_f32_16x16x32_bf16 v[20:23], v[174:177], v[206:209], v[20:23]
	v_mfma_f32_16x16x32_bf16 v[16:19], v[182:185], v[206:209], v[16:19]
	v_mfma_f32_16x16x32_bf16 v[4:7], v[174:177], v[218:221], v[4:7]
	v_mfma_f32_16x16x32_bf16 v[0:3], v[182:185], v[218:221], v[0:3]
	v_mfma_f32_16x16x32_bf16 v[52:55], v[178:181], v[194:197], v[52:55]
	v_mfma_f32_16x16x32_bf16 v[48:51], v[186:189], v[194:197], v[48:51]
	v_mfma_f32_16x16x32_bf16 v[36:39], v[178:181], v[202:205], v[36:39]
	v_mfma_f32_16x16x32_bf16 v[32:35], v[186:189], v[202:205], v[32:35]
	v_mfma_f32_16x16x32_bf16 v[20:23], v[178:181], v[214:217], v[20:23]
	v_mfma_f32_16x16x32_bf16 v[16:19], v[186:189], v[214:217], v[16:19]
	v_mfma_f32_16x16x32_bf16 v[4:7], v[178:181], v[222:225], v[4:7]
	v_mfma_f32_16x16x32_bf16 v[0:3], v[186:189], v[222:225], v[0:3]
	s_barrier
	s_setprio 0
	s_add_i32 s90, s90, 2
	s_add_u32 s74, s74, 0x100
	s_addc_u32 s75, s75, 0
	s_add_u32 s65, s65, 0x100
	s_addc_u32 s71, s71, 0
	s_cmp_gt_u32 s90, 29
	s_cbranch_scc0 .LBB0_272
	s_and_b64 vcc, exec, s[36:37]
	s_cbranch_vccz .LBB0_275
	s_barrier

.LBB0_542:
	s_ashr_i32 s35, s34, 31
	s_lshl_b64 s[0:1], s[34:35], 20
	s_add_u32 s36, s29, s0
	s_addc_u32 s37, s30, s1
	s_and_b64 s[0:1], s[6:7], exec
	s_cselect_b32 s0, s37, s43
	s_cselect_b32 s1, s36, s42
	s_ashr_i32 s25, s24, 31
	s_lshl_b64 s[38:39], s[24:25], 20
	s_add_u32 s38, s27, s38
	s_addc_u32 s39, s28, s39
	s_and_b64 s[46:47], s[6:7], exec
	s_cselect_b32 s3, s39, s45
	s_cselect_b32 s9, s38, s44
	s_add_u32 s42, s42, 0x80080
	s_addc_u32 s43, s43, 0
	s_add_u32 s25, s44, 0x100
	s_addc_u32 s35, s45, 0
	s_mov_b32 s58, -2
	s_waitcnt lgkmcnt(0)
	s_waitcnt vmcnt(0)
	ds_read_b128 v[128:131], v216
	ds_read_b128 v[132:135], v216 offset:1024
	ds_read_b128 v[136:139], v216 offset:2048
	ds_read_b128 v[140:143], v216 offset:3072
	ds_read_b128 v[144:147], v217
	ds_read_b128 v[148:151], v217 offset:1024
	ds_read_b128 v[152:155], v217 offset:2048
	ds_read_b128 v[156:159], v217 offset:3072
	s_add_u32 s44, s42, 0xfff80080
	s_addc_u32 s45, s43, -1
	s_cmp_eq_u32 s58, 28
	s_cselect_b32 s47, s0, s45
	s_cselect_b32 s46, s1, s44
	s_cselect_b32 s45, s3, s35
	s_cselect_b32 s44, s9, s25
	s_add_i32 m0, s41, 0xc000
	ds_read_b128 v[160:163], v218
	ds_read_b128 v[164:167], v218 offset:1024
	ds_read_b128 v[168:171], v218 offset:2048
	ds_read_b128 v[172:175], v218 offset:3072
	ds_read_b128 v[192:195], v218 offset:4096
	ds_read_b128 v[196:199], v218 offset:5120
	ds_read_b128 v[200:203], v218 offset:6144
	global_load_lds_dwordx4 v184, s[42:43]
	s_add_i32 m0, s41, 0xe000
	ds_read_b128 v[204:207], v218 offset:7168
	global_load_lds_dwordx4 v186, s[42:43]
	s_waitcnt vmcnt(8)
	s_waitcnt lgkmcnt(0)
	s_setprio 1
	s_barrier
	v_mfma_f32_16x16x32_bf16 v[124:127], v[128:131], v[160:163], 0
	v_mfma_f32_16x16x32_bf16 v[120:123], v[136:139], v[160:163], 0
	v_mfma_f32_16x16x32_bf16 v[108:111], v[128:131], v[168:171], 0
	v_mfma_f32_16x16x32_bf16 v[104:107], v[136:139], v[168:171], 0
	v_mfma_f32_16x16x32_bf16 v[92:95], v[128:131], v[192:195], 0
	v_mfma_f32_16x16x32_bf16 v[88:91], v[136:139], v[192:195], 0
	v_mfma_f32_16x16x32_bf16 v[76:79], v[128:131], v[200:203], 0
	v_mfma_f32_16x16x32_bf16 v[72:75], v[136:139], v[200:203], 0
	v_mfma_f32_16x16x32_bf16 v[124:127], v[132:135], v[164:167], v[124:127]
	v_mfma_f32_16x16x32_bf16 v[120:123], v[140:143], v[164:167], v[120:123]
	v_mfma_f32_16x16x32_bf16 v[108:111], v[132:135], v[172:175], v[108:111]
	v_mfma_f32_16x16x32_bf16 v[104:107], v[140:143], v[172:175], v[104:107]
	v_mfma_f32_16x16x32_bf16 v[92:95], v[132:135], v[196:199], v[92:95]
	v_mfma_f32_16x16x32_bf16 v[88:91], v[140:143], v[196:199], v[88:91]
	v_mfma_f32_16x16x32_bf16 v[76:79], v[132:135], v[204:207], v[76:79]
	v_mfma_f32_16x16x32_bf16 v[72:75], v[140:143], v[204:207], v[72:75]
	s_setprio 0
	s_setprio 1
	v_mfma_f32_16x16x32_bf16 v[116:119], v[144:147], v[160:163], 0
	v_mfma_f32_16x16x32_bf16 v[112:115], v[152:155], v[160:163], 0
	v_mfma_f32_16x16x32_bf16 v[100:103], v[144:147], v[168:171], 0
	v_mfma_f32_16x16x32_bf16 v[96:99], v[152:155], v[168:171], 0
	v_mfma_f32_16x16x32_bf16 v[84:87], v[144:147], v[192:195], 0
	v_mfma_f32_16x16x32_bf16 v[80:83], v[152:155], v[192:195], 0
	v_mfma_f32_16x16x32_bf16 v[68:71], v[144:147], v[200:203], 0
	v_mfma_f32_16x16x32_bf16 v[64:67], v[152:155], v[200:203], 0
	v_mfma_f32_16x16x32_bf16 v[116:119], v[148:151], v[164:167], v[116:119]
	v_mfma_f32_16x16x32_bf16 v[112:115], v[156:159], v[164:167], v[112:115]
	v_mfma_f32_16x16x32_bf16 v[100:103], v[148:151], v[172:175], v[100:103]
	v_mfma_f32_16x16x32_bf16 v[96:99], v[156:159], v[172:175], v[96:99]
	v_mfma_f32_16x16x32_bf16 v[84:87], v[148:151], v[196:199], v[84:87]
	v_mfma_f32_16x16x32_bf16 v[80:83], v[156:159], v[196:199], v[80:83]
	v_mfma_f32_16x16x32_bf16 v[68:71], v[148:151], v[204:207], v[68:71]
	v_mfma_f32_16x16x32_bf16 v[64:67], v[156:159], v[204:207], v[64:67]
	s_barrier
	s_setprio 0
	s_add_i32 s59, s55, s31
	s_add_u32 s98, s44, s20
	s_addc_u32 s99, s45, s21
	s_mov_b32 m0, s59
	ds_read_b128 v[160:163], v218 offset:16384
	ds_read_b128 v[164:167], v218 offset:17408
	ds_read_b128 v[168:171], v218 offset:18432
	ds_read_b128 v[172:175], v218 offset:19456
	ds_read_b128 v[192:195], v218 offset:20480
	global_load_lds_dwordx4 v178, s[44:45]
	s_add_i32 m0, s59, 0x2000
	s_add_u32 s60, s44, 0x80000
	s_addc_u32 s61, s45, 0
	s_add_i32 s59, s56, s31
	global_load_lds_dwordx4 v182, s[44:45]
	s_mov_b32 m0, s59
	s_add_u32 s100, s46, s20
	s_addc_u32 s101, s47, s21
	global_load_lds_dwordx4 v178, s[60:61]
	s_add_i32 m0, s59, 0x2000
	ds_read_b128 v[204:207], v218 offset:23552
	global_load_lds_dwordx4 v182, s[60:61]
	s_mov_b32 m0, s41
	ds_read_b128 v[200:203], v218 offset:22528
	global_load_lds_dwordx4 v176, s[46:47]
	s_mov_b32 m0, s48
	ds_read_b128 v[196:199], v218 offset:21504
	global_load_lds_dwordx4 v180, s[46:47]
	s_waitcnt vmcnt(8)
	s_waitcnt lgkmcnt(0)
	s_setprio 1
	s_barrier
	v_mfma_f32_16x16x32_bf16 v[60:63], v[128:131], v[160:163], 0
	v_mfma_f32_16x16x32_bf16 v[56:59], v[136:139], v[160:163], 0
	v_mfma_f32_16x16x32_bf16 v[44:47], v[128:131], v[168:171], 0
	v_mfma_f32_16x16x32_bf16 v[40:43], v[136:139], v[168:171], 0
	v_mfma_f32_16x16x32_bf16 v[28:31], v[128:131], v[192:195], 0
	v_mfma_f32_16x16x32_bf16 v[24:27], v[136:139], v[192:195], 0
	v_mfma_f32_16x16x32_bf16 v[12:15], v[128:131], v[200:203], 0
	v_mfma_f32_16x16x32_bf16 v[8:11], v[136:139], v[200:203], 0
	v_mfma_f32_16x16x32_bf16 v[60:63], v[132:135], v[164:167], v[60:63]
	v_mfma_f32_16x16x32_bf16 v[56:59], v[140:143], v[164:167], v[56:59]
	v_mfma_f32_16x16x32_bf16 v[44:47], v[132:135], v[172:175], v[44:47]
	v_mfma_f32_16x16x32_bf16 v[40:43], v[140:143], v[172:175], v[40:43]
	v_mfma_f32_16x16x32_bf16 v[28:31], v[132:135], v[196:199], v[28:31]
	v_mfma_f32_16x16x32_bf16 v[24:27], v[140:143], v[196:199], v[24:27]
	v_mfma_f32_16x16x32_bf16 v[12:15], v[132:135], v[204:207], v[12:15]
	v_mfma_f32_16x16x32_bf16 v[8:11], v[140:143], v[204:207], v[8:11]
	s_setprio 0
	s_setprio 1
	v_mfma_f32_16x16x32_bf16 v[52:55], v[144:147], v[160:163], 0
	v_mfma_f32_16x16x32_bf16 v[48:51], v[152:155], v[160:163], 0
	v_mfma_f32_16x16x32_bf16 v[36:39], v[144:147], v[168:171], 0
	v_mfma_f32_16x16x32_bf16 v[32:35], v[152:155], v[168:171], 0
	v_mfma_f32_16x16x32_bf16 v[20:23], v[144:147], v[192:195], 0
	v_mfma_f32_16x16x32_bf16 v[16:19], v[152:155], v[192:195], 0
	v_mfma_f32_16x16x32_bf16 v[4:7], v[144:147], v[200:203], 0
	v_mfma_f32_16x16x32_bf16 v[0:3], v[152:155], v[200:203], 0
	v_mfma_f32_16x16x32_bf16 v[52:55], v[148:151], v[164:167], v[52:55]
	v_mfma_f32_16x16x32_bf16 v[48:51], v[156:159], v[164:167], v[48:51]
	v_mfma_f32_16x16x32_bf16 v[36:39], v[148:151], v[172:175], v[36:39]
	v_mfma_f32_16x16x32_bf16 v[32:35], v[156:159], v[172:175], v[32:35]
	v_mfma_f32_16x16x32_bf16 v[20:23], v[148:151], v[196:199], v[20:23]
	v_mfma_f32_16x16x32_bf16 v[16:19], v[156:159], v[196:199], v[16:19]
	v_mfma_f32_16x16x32_bf16 v[4:7], v[148:151], v[204:207], v[4:7]
	v_mfma_f32_16x16x32_bf16 v[0:3], v[156:159], v[204:207], v[0:3]
	s_barrier
	s_setprio 0
	s_add_i32 s59, 0, 0x18000
	s_add_i32 s60, 0, 0x1c000
	v_add_u32_e32 v140, s59, v214
	v_add_u32_e32 v156, s60, v214
	ds_read_b128 v[128:131], v140
	ds_read_b128 v[132:135], v140 offset:1024
	ds_read_b128 v[136:139], v140 offset:2048
	ds_read_b128 v[140:143], v140 offset:3072
	ds_read_b128 v[144:147], v156
	ds_read_b128 v[148:151], v156 offset:1024
	ds_read_b128 v[152:155], v156 offset:2048
	ds_read_b128 v[156:159], v156 offset:3072
	s_add_u32 s46, s46, 0x80000
	s_addc_u32 s47, s47, 0
	s_mov_b32 m0, s49
	ds_read_b128 v[160:163], v218 offset:32768
	ds_read_b128 v[164:167], v218 offset:33792
	ds_read_b128 v[168:171], v218 offset:34816
	ds_read_b128 v[172:175], v218 offset:35840
	ds_read_b128 v[192:195], v218 offset:36864
	ds_read_b128 v[196:199], v218 offset:37888
	ds_read_b128 v[200:203], v218 offset:38912
	global_load_lds_dwordx4 v176, s[46:47]
	s_mov_b32 m0, s50
	ds_read_b128 v[204:207], v218 offset:39936
	global_load_lds_dwordx4 v180, s[46:47]
	s_waitcnt vmcnt(8)
	s_waitcnt lgkmcnt(0)
	s_setprio 1
	s_barrier
	v_mfma_f32_16x16x32_bf16 v[124:127], v[128:131], v[160:163], v[124:127]
	v_mfma_f32_16x16x32_bf16 v[120:123], v[136:139], v[160:163], v[120:123]
	v_mfma_f32_16x16x32_bf16 v[108:111], v[128:131], v[168:171], v[108:111]
	v_mfma_f32_16x16x32_bf16 v[104:107], v[136:139], v[168:171], v[104:107]
	v_mfma_f32_16x16x32_bf16 v[92:95], v[128:131], v[192:195], v[92:95]
	v_mfma_f32_16x16x32_bf16 v[88:91], v[136:139], v[192:195], v[88:91]
	v_mfma_f32_16x16x32_bf16 v[76:79], v[128:131], v[200:203], v[76:79]
	v_mfma_f32_16x16x32_bf16 v[72:75], v[136:139], v[200:203], v[72:75]
	v_mfma_f32_16x16x32_bf16 v[124:127], v[132:135], v[164:167], v[124:127]
	v_mfma_f32_16x16x32_bf16 v[120:123], v[140:143], v[164:167], v[120:123]
	v_mfma_f32_16x16x32_bf16 v[108:111], v[132:135], v[172:175], v[108:111]
	v_mfma_f32_16x16x32_bf16 v[104:107], v[140:143], v[172:175], v[104:107]
	v_mfma_f32_16x16x32_bf16 v[92:95], v[132:135], v[196:199], v[92:95]
	v_mfma_f32_16x16x32_bf16 v[88:91], v[140:143], v[196:199], v[88:91]
	v_mfma_f32_16x16x32_bf16 v[76:79], v[132:135], v[204:207], v[76:79]
	v_mfma_f32_16x16x32_bf16 v[72:75], v[140:143], v[204:207], v[72:75]
	s_setprio 0
	s_setprio 1
	v_mfma_f32_16x16x32_bf16 v[116:119], v[144:147], v[160:163], v[116:119]
	v_mfma_f32_16x16x32_bf16 v[112:115], v[152:155], v[160:163], v[112:115]
	v_mfma_f32_16x16x32_bf16 v[100:103], v[144:147], v[168:171], v[100:103]
	v_mfma_f32_16x16x32_bf16 v[96:99], v[152:155], v[168:171], v[96:99]
	v_mfma_f32_16x16x32_bf16 v[84:87], v[144:147], v[192:195], v[84:87]
	v_mfma_f32_16x16x32_bf16 v[80:83], v[152:155], v[192:195], v[80:83]
	v_mfma_f32_16x16x32_bf16 v[68:71], v[144:147], v[200:203], v[68:71]
	v_mfma_f32_16x16x32_bf16 v[64:67], v[152:155], v[200:203], v[64:67]
	v_mfma_f32_16x16x32_bf16 v[116:119], v[148:151], v[164:167], v[116:119]
	v_mfma_f32_16x16x32_bf16 v[112:115], v[156:159], v[164:167], v[112:115]
	v_mfma_f32_16x16x32_bf16 v[100:103], v[148:151], v[172:175], v[100:103]
	v_mfma_f32_16x16x32_bf16 v[96:99], v[156:159], v[172:175], v[96:99]
	v_mfma_f32_16x16x32_bf16 v[84:87], v[148:151], v[196:199], v[84:87]
	v_mfma_f32_16x16x32_bf16 v[80:83], v[156:159], v[196:199], v[80:83]
	v_mfma_f32_16x16x32_bf16 v[68:71], v[148:151], v[204:207], v[68:71]
	v_mfma_f32_16x16x32_bf16 v[64:67], v[156:159], v[204:207], v[64:67]
	s_barrier
	s_setprio 0
	s_add_i32 s46, s59, s31
	s_mov_b32 m0, s46
	ds_read_b128 v[160:163], v218 offset:49152
	ds_read_b128 v[164:167], v218 offset:50176
	ds_read_b128 v[168:171], v218 offset:51200
	ds_read_b128 v[172:175], v218 offset:52224
	global_load_lds_dwordx4 v178, s[98:99]
	s_add_i32 m0, s46, 0x2000
	s_add_u32 s44, s44, 0x80080
	s_addc_u32 s45, s45, 0
	s_add_i32 s46, s60, s31
	global_load_lds_dwordx4 v182, s[98:99]
	s_mov_b32 m0, s46
	ds_read_b128 v[204:207], v218 offset:56320
	global_load_lds_dwordx4 v178, s[44:45]
	s_add_i32 m0, s46, 0x2000
	ds_read_b128 v[200:203], v218 offset:55296
	global_load_lds_dwordx4 v182, s[44:45]
	s_mov_b32 m0, s52
	ds_read_b128 v[196:199], v218 offset:54272
	global_load_lds_dwordx4 v176, s[100:101]
	s_mov_b32 m0, s53
	ds_read_b128 v[192:195], v218 offset:53248
	global_load_lds_dwordx4 v180, s[100:101]
	s_waitcnt vmcnt(8)
	s_waitcnt lgkmcnt(0)
	s_setprio 1
	s_barrier
	v_mfma_f32_16x16x32_bf16 v[60:63], v[128:131], v[160:163], v[60:63]
	v_mfma_f32_16x16x32_bf16 v[56:59], v[136:139], v[160:163], v[56:59]
	v_mfma_f32_16x16x32_bf16 v[44:47], v[128:131], v[168:171], v[44:47]
	v_mfma_f32_16x16x32_bf16 v[40:43], v[136:139], v[168:171], v[40:43]
	v_mfma_f32_16x16x32_bf16 v[28:31], v[128:131], v[192:195], v[28:31]
	v_mfma_f32_16x16x32_bf16 v[24:27], v[136:139], v[192:195], v[24:27]
	v_mfma_f32_16x16x32_bf16 v[12:15], v[128:131], v[200:203], v[12:15]
	v_mfma_f32_16x16x32_bf16 v[8:11], v[136:139], v[200:203], v[8:11]
	v_mfma_f32_16x16x32_bf16 v[60:63], v[132:135], v[164:167], v[60:63]
	v_mfma_f32_16x16x32_bf16 v[56:59], v[140:143], v[164:167], v[56:59]
	v_mfma_f32_16x16x32_bf16 v[44:47], v[132:135], v[172:175], v[44:47]
	v_mfma_f32_16x16x32_bf16 v[40:43], v[140:143], v[172:175], v[40:43]
	v_mfma_f32_16x16x32_bf16 v[28:31], v[132:135], v[196:199], v[28:31]
	v_mfma_f32_16x16x32_bf16 v[24:27], v[140:143], v[196:199], v[24:27]
	v_mfma_f32_16x16x32_bf16 v[12:15], v[132:135], v[204:207], v[12:15]
	v_mfma_f32_16x16x32_bf16 v[8:11], v[140:143], v[204:207], v[8:11]
	s_setprio 0
	s_setprio 1
	v_mfma_f32_16x16x32_bf16 v[52:55], v[144:147], v[160:163], v[52:55]
	v_mfma_f32_16x16x32_bf16 v[48:51], v[152:155], v[160:163], v[48:51]
	v_mfma_f32_16x16x32_bf16 v[36:39], v[144:147], v[168:171], v[36:39]
	v_mfma_f32_16x16x32_bf16 v[32:35], v[152:155], v[168:171], v[32:35]
	v_mfma_f32_16x16x32_bf16 v[20:23], v[144:147], v[192:195], v[20:23]
	v_mfma_f32_16x16x32_bf16 v[16:19], v[152:155], v[192:195], v[16:19]
	v_mfma_f32_16x16x32_bf16 v[4:7], v[144:147], v[200:203], v[4:7]
	v_mfma_f32_16x16x32_bf16 v[0:3], v[152:155], v[200:203], v[0:3]
	v_mfma_f32_16x16x32_bf16 v[52:55], v[148:151], v[164:167], v[52:55]
	v_mfma_f32_16x16x32_bf16 v[48:51], v[156:159], v[164:167], v[48:51]
	v_mfma_f32_16x16x32_bf16 v[36:39], v[148:151], v[172:175], v[36:39]
	v_mfma_f32_16x16x32_bf16 v[32:35], v[156:159], v[172:175], v[32:35]
	v_mfma_f32_16x16x32_bf16 v[20:23], v[148:151], v[196:199], v[20:23]
	v_mfma_f32_16x16x32_bf16 v[16:19], v[156:159], v[196:199], v[16:19]
	v_mfma_f32_16x16x32_bf16 v[4:7], v[148:151], v[204:207], v[4:7]
	v_mfma_f32_16x16x32_bf16 v[0:3], v[156:159], v[204:207], v[0:3]
	s_barrier
	s_setprio 0
	s_add_i32 s58, s58, 2
	s_add_u32 s42, s42, 0x100
	s_addc_u32 s43, s43, 0
	s_add_u32 s25, s25, 0x100
	s_addc_u32 s35, s35, 0
	s_cmp_gt_u32 s58, 29
.LBB0_543:
	ds_read_b128 v[128:131], v216
	ds_read_b128 v[132:135], v216 offset:1024
	ds_read_b128 v[136:139], v216 offset:2048
	ds_read_b128 v[140:143], v216 offset:3072
	ds_read_b128 v[144:147], v217
	ds_read_b128 v[148:151], v217 offset:1024
	ds_read_b128 v[152:155], v217 offset:2048
	ds_read_b128 v[156:159], v217 offset:3072
	s_add_u32 s44, s42, 0xfff80080
	s_addc_u32 s45, s43, -1
	s_cmp_eq_u32 s58, 28
	s_cselect_b32 s47, s0, s45
	s_cselect_b32 s46, s1, s44
	s_cselect_b32 s45, s3, s35
	s_cselect_b32 s44, s9, s25
	s_add_i32 m0, s41, 0xc000
	ds_read_b128 v[160:163], v218
	ds_read_b128 v[164:167], v218 offset:1024
	ds_read_b128 v[168:171], v218 offset:2048
	ds_read_b128 v[172:175], v218 offset:3072
	ds_read_b128 v[192:195], v218 offset:4096
	ds_read_b128 v[196:199], v218 offset:5120
	ds_read_b128 v[200:203], v218 offset:6144
	global_load_lds_dwordx4 v184, s[42:43]
	s_add_i32 m0, s41, 0xe000
	ds_read_b128 v[204:207], v218 offset:7168
	global_load_lds_dwordx4 v186, s[42:43]
	s_waitcnt vmcnt(8)
	s_waitcnt lgkmcnt(0)
	s_setprio 1
	s_barrier
	v_mfma_f32_16x16x32_bf16 v[124:127], v[128:131], v[160:163], v[124:127]
	v_mfma_f32_16x16x32_bf16 v[120:123], v[136:139], v[160:163], v[120:123]
	v_mfma_f32_16x16x32_bf16 v[108:111], v[128:131], v[168:171], v[108:111]
	v_mfma_f32_16x16x32_bf16 v[104:107], v[136:139], v[168:171], v[104:107]
	v_mfma_f32_16x16x32_bf16 v[92:95], v[128:131], v[192:195], v[92:95]
	v_mfma_f32_16x16x32_bf16 v[88:91], v[136:139], v[192:195], v[88:91]
	v_mfma_f32_16x16x32_bf16 v[76:79], v[128:131], v[200:203], v[76:79]
	v_mfma_f32_16x16x32_bf16 v[72:75], v[136:139], v[200:203], v[72:75]
	v_mfma_f32_16x16x32_bf16 v[124:127], v[132:135], v[164:167], v[124:127]
	v_mfma_f32_16x16x32_bf16 v[120:123], v[140:143], v[164:167], v[120:123]
	v_mfma_f32_16x16x32_bf16 v[108:111], v[132:135], v[172:175], v[108:111]
	v_mfma_f32_16x16x32_bf16 v[104:107], v[140:143], v[172:175], v[104:107]
	v_mfma_f32_16x16x32_bf16 v[92:95], v[132:135], v[196:199], v[92:95]
	v_mfma_f32_16x16x32_bf16 v[88:91], v[140:143], v[196:199], v[88:91]
	v_mfma_f32_16x16x32_bf16 v[76:79], v[132:135], v[204:207], v[76:79]
	v_mfma_f32_16x16x32_bf16 v[72:75], v[140:143], v[204:207], v[72:75]
	s_setprio 0
	s_setprio 1
	v_mfma_f32_16x16x32_bf16 v[116:119], v[144:147], v[160:163], v[116:119]
	v_mfma_f32_16x16x32_bf16 v[112:115], v[152:155], v[160:163], v[112:115]
	v_mfma_f32_16x16x32_bf16 v[100:103], v[144:147], v[168:171], v[100:103]
	v_mfma_f32_16x16x32_bf16 v[96:99], v[152:155], v[168:171], v[96:99]
	v_mfma_f32_16x16x32_bf16 v[84:87], v[144:147], v[192:195], v[84:87]
	v_mfma_f32_16x16x32_bf16 v[80:83], v[152:155], v[192:195], v[80:83]
	v_mfma_f32_16x16x32_bf16 v[68:71], v[144:147], v[200:203], v[68:71]
	v_mfma_f32_16x16x32_bf16 v[64:67], v[152:155], v[200:203], v[64:67]
	v_mfma_f32_16x16x32_bf16 v[116:119], v[148:151], v[164:167], v[116:119]
	v_mfma_f32_16x16x32_bf16 v[112:115], v[156:159], v[164:167], v[112:115]
	v_mfma_f32_16x16x32_bf16 v[100:103], v[148:151], v[172:175], v[100:103]
	v_mfma_f32_16x16x32_bf16 v[96:99], v[156:159], v[172:175], v[96:99]
	v_mfma_f32_16x16x32_bf16 v[84:87], v[148:151], v[196:199], v[84:87]
	v_mfma_f32_16x16x32_bf16 v[80:83], v[156:159], v[196:199], v[80:83]
	v_mfma_f32_16x16x32_bf16 v[68:71], v[148:151], v[204:207], v[68:71]
	v_mfma_f32_16x16x32_bf16 v[64:67], v[156:159], v[204:207], v[64:67]
	s_barrier
	s_setprio 0
	s_add_i32 s59, s55, s31
	s_add_u32 s98, s44, s20
	s_addc_u32 s99, s45, s21
	s_mov_b32 m0, s59
	ds_read_b128 v[160:163], v218 offset:16384
	ds_read_b128 v[164:167], v218 offset:17408
	ds_read_b128 v[168:171], v218 offset:18432
	ds_read_b128 v[172:175], v218 offset:19456
	ds_read_b128 v[192:195], v218 offset:20480
	global_load_lds_dwordx4 v178, s[44:45]
	s_add_i32 m0, s59, 0x2000
	s_add_u32 s60, s44, 0x80000
	s_addc_u32 s61, s45, 0
	s_add_i32 s59, s56, s31
	global_load_lds_dwordx4 v182, s[44:45]
	s_mov_b32 m0, s59
	s_add_u32 s100, s46, s20
	s_addc_u32 s101, s47, s21
	global_load_lds_dwordx4 v178, s[60:61]
	s_add_i32 m0, s59, 0x2000
	ds_read_b128 v[204:207], v218 offset:23552
	global_load_lds_dwordx4 v182, s[60:61]
	s_mov_b32 m0, s41
	ds_read_b128 v[200:203], v218 offset:22528
	global_load_lds_dwordx4 v176, s[46:47]
	s_mov_b32 m0, s48
	ds_read_b128 v[196:199], v218 offset:21504
	global_load_lds_dwordx4 v180, s[46:47]
	s_waitcnt vmcnt(8)
	s_waitcnt lgkmcnt(0)
	s_setprio 1
	s_barrier
	v_mfma_f32_16x16x32_bf16 v[60:63], v[128:131], v[160:163], v[60:63]
	v_mfma_f32_16x16x32_bf16 v[56:59], v[136:139], v[160:163], v[56:59]
	v_mfma_f32_16x16x32_bf16 v[44:47], v[128:131], v[168:171], v[44:47]
	v_mfma_f32_16x16x32_bf16 v[40:43], v[136:139], v[168:171], v[40:43]
	v_mfma_f32_16x16x32_bf16 v[28:31], v[128:131], v[192:195], v[28:31]
	v_mfma_f32_16x16x32_bf16 v[24:27], v[136:139], v[192:195], v[24:27]
	v_mfma_f32_16x16x32_bf16 v[12:15], v[128:131], v[200:203], v[12:15]
	v_mfma_f32_16x16x32_bf16 v[8:11], v[136:139], v[200:203], v[8:11]
	v_mfma_f32_16x16x32_bf16 v[60:63], v[132:135], v[164:167], v[60:63]
	v_mfma_f32_16x16x32_bf16 v[56:59], v[140:143], v[164:167], v[56:59]
	v_mfma_f32_16x16x32_bf16 v[44:47], v[132:135], v[172:175], v[44:47]
	v_mfma_f32_16x16x32_bf16 v[40:43], v[140:143], v[172:175], v[40:43]
	v_mfma_f32_16x16x32_bf16 v[28:31], v[132:135], v[196:199], v[28:31]
	v_mfma_f32_16x16x32_bf16 v[24:27], v[140:143], v[196:199], v[24:27]
	v_mfma_f32_16x16x32_bf16 v[12:15], v[132:135], v[204:207], v[12:15]
	v_mfma_f32_16x16x32_bf16 v[8:11], v[140:143], v[204:207], v[8:11]
	s_setprio 0
	s_setprio 1
	v_mfma_f32_16x16x32_bf16 v[52:55], v[144:147], v[160:163], v[52:55]
	v_mfma_f32_16x16x32_bf16 v[48:51], v[152:155], v[160:163], v[48:51]
	v_mfma_f32_16x16x32_bf16 v[36:39], v[144:147], v[168:171], v[36:39]
	v_mfma_f32_16x16x32_bf16 v[32:35], v[152:155], v[168:171], v[32:35]
	v_mfma_f32_16x16x32_bf16 v[20:23], v[144:147], v[192:195], v[20:23]
	v_mfma_f32_16x16x32_bf16 v[16:19], v[152:155], v[192:195], v[16:19]
	v_mfma_f32_16x16x32_bf16 v[4:7], v[144:147], v[200:203], v[4:7]
	v_mfma_f32_16x16x32_bf16 v[0:3], v[152:155], v[200:203], v[0:3]
	v_mfma_f32_16x16x32_bf16 v[52:55], v[148:151], v[164:167], v[52:55]
	v_mfma_f32_16x16x32_bf16 v[48:51], v[156:159], v[164:167], v[48:51]
	v_mfma_f32_16x16x32_bf16 v[36:39], v[148:151], v[172:175], v[36:39]
	v_mfma_f32_16x16x32_bf16 v[32:35], v[156:159], v[172:175], v[32:35]
	v_mfma_f32_16x16x32_bf16 v[20:23], v[148:151], v[196:199], v[20:23]
	v_mfma_f32_16x16x32_bf16 v[16:19], v[156:159], v[196:199], v[16:19]
	v_mfma_f32_16x16x32_bf16 v[4:7], v[148:151], v[204:207], v[4:7]
	v_mfma_f32_16x16x32_bf16 v[0:3], v[156:159], v[204:207], v[0:3]
	s_barrier
	s_setprio 0
	s_add_i32 s59, 0, 0x18000
	s_add_i32 s60, 0, 0x1c000
	v_add_u32_e32 v140, s59, v214
	v_add_u32_e32 v156, s60, v214
	ds_read_b128 v[128:131], v140
	ds_read_b128 v[132:135], v140 offset:1024
	ds_read_b128 v[136:139], v140 offset:2048
	ds_read_b128 v[140:143], v140 offset:3072
	ds_read_b128 v[144:147], v156
	ds_read_b128 v[148:151], v156 offset:1024
	ds_read_b128 v[152:155], v156 offset:2048
	ds_read_b128 v[156:159], v156 offset:3072
	s_add_u32 s46, s46, 0x80000
	s_addc_u32 s47, s47, 0
	s_mov_b32 m0, s49
	ds_read_b128 v[160:163], v218 offset:32768
	ds_read_b128 v[164:167], v218 offset:33792
	ds_read_b128 v[168:171], v218 offset:34816
	ds_read_b128 v[172:175], v218 offset:35840
	ds_read_b128 v[192:195], v218 offset:36864
	ds_read_b128 v[196:199], v218 offset:37888
	ds_read_b128 v[200:203], v218 offset:38912
	global_load_lds_dwordx4 v176, s[46:47]
	s_mov_b32 m0, s50
	ds_read_b128 v[204:207], v218 offset:39936
	global_load_lds_dwordx4 v180, s[46:47]
	s_waitcnt vmcnt(8)
	s_waitcnt lgkmcnt(0)
	s_setprio 1
	s_barrier
	v_mfma_f32_16x16x32_bf16 v[124:127], v[128:131], v[160:163], v[124:127]
	v_mfma_f32_16x16x32_bf16 v[120:123], v[136:139], v[160:163], v[120:123]
	v_mfma_f32_16x16x32_bf16 v[108:111], v[128:131], v[168:171], v[108:111]
	v_mfma_f32_16x16x32_bf16 v[104:107], v[136:139], v[168:171], v[104:107]
	v_mfma_f32_16x16x32_bf16 v[92:95], v[128:131], v[192:195], v[92:95]
	v_mfma_f32_16x16x32_bf16 v[88:91], v[136:139], v[192:195], v[88:91]
	v_mfma_f32_16x16x32_bf16 v[76:79], v[128:131], v[200:203], v[76:79]
	v_mfma_f32_16x16x32_bf16 v[72:75], v[136:139], v[200:203], v[72:75]
	v_mfma_f32_16x16x32_bf16 v[124:127], v[132:135], v[164:167], v[124:127]
	v_mfma_f32_16x16x32_bf16 v[120:123], v[140:143], v[164:167], v[120:123]
	v_mfma_f32_16x16x32_bf16 v[108:111], v[132:135], v[172:175], v[108:111]
	v_mfma_f32_16x16x32_bf16 v[104:107], v[140:143], v[172:175], v[104:107]
	v_mfma_f32_16x16x32_bf16 v[92:95], v[132:135], v[196:199], v[92:95]
	v_mfma_f32_16x16x32_bf16 v[88:91], v[140:143], v[196:199], v[88:91]
	v_mfma_f32_16x16x32_bf16 v[76:79], v[132:135], v[204:207], v[76:79]
	v_mfma_f32_16x16x32_bf16 v[72:75], v[140:143], v[204:207], v[72:75]
	s_setprio 0
	s_setprio 1
	v_mfma_f32_16x16x32_bf16 v[116:119], v[144:147], v[160:163], v[116:119]
	v_mfma_f32_16x16x32_bf16 v[112:115], v[152:155], v[160:163], v[112:115]
	v_mfma_f32_16x16x32_bf16 v[100:103], v[144:147], v[168:171], v[100:103]
	v_mfma_f32_16x16x32_bf16 v[96:99], v[152:155], v[168:171], v[96:99]
	v_mfma_f32_16x16x32_bf16 v[84:87], v[144:147], v[192:195], v[84:87]
	v_mfma_f32_16x16x32_bf16 v[80:83], v[152:155], v[192:195], v[80:83]
	v_mfma_f32_16x16x32_bf16 v[68:71], v[144:147], v[200:203], v[68:71]
	v_mfma_f32_16x16x32_bf16 v[64:67], v[152:155], v[200:203], v[64:67]
	v_mfma_f32_16x16x32_bf16 v[116:119], v[148:151], v[164:167], v[116:119]
	v_mfma_f32_16x16x32_bf16 v[112:115], v[156:159], v[164:167], v[112:115]
	v_mfma_f32_16x16x32_bf16 v[100:103], v[148:151], v[172:175], v[100:103]
	v_mfma_f32_16x16x32_bf16 v[96:99], v[156:159], v[172:175], v[96:99]
	v_mfma_f32_16x16x32_bf16 v[84:87], v[148:151], v[196:199], v[84:87]
	v_mfma_f32_16x16x32_bf16 v[80:83], v[156:159], v[196:199], v[80:83]
	v_mfma_f32_16x16x32_bf16 v[68:71], v[148:151], v[204:207], v[68:71]
	v_mfma_f32_16x16x32_bf16 v[64:67], v[156:159], v[204:207], v[64:67]
	s_barrier
	s_setprio 0
	s_add_i32 s46, s59, s31
	s_mov_b32 m0, s46
	ds_read_b128 v[160:163], v218 offset:49152
	ds_read_b128 v[164:167], v218 offset:50176
	ds_read_b128 v[168:171], v218 offset:51200
	ds_read_b128 v[172:175], v218 offset:52224
	global_load_lds_dwordx4 v178, s[98:99]
	s_add_i32 m0, s46, 0x2000
	s_add_u32 s44, s44, 0x80080
	s_addc_u32 s45, s45, 0
	s_add_i32 s46, s60, s31
	global_load_lds_dwordx4 v182, s[98:99]
	s_mov_b32 m0, s46
	ds_read_b128 v[204:207], v218 offset:56320
	global_load_lds_dwordx4 v178, s[44:45]
	s_add_i32 m0, s46, 0x2000
	ds_read_b128 v[200:203], v218 offset:55296
	global_load_lds_dwordx4 v182, s[44:45]
	s_mov_b32 m0, s52
	ds_read_b128 v[196:199], v218 offset:54272
	global_load_lds_dwordx4 v176, s[100:101]
	s_mov_b32 m0, s53
	ds_read_b128 v[192:195], v218 offset:53248
	global_load_lds_dwordx4 v180, s[100:101]
	s_waitcnt vmcnt(8)
	s_waitcnt lgkmcnt(0)
	s_setprio 1
	s_barrier
	v_mfma_f32_16x16x32_bf16 v[60:63], v[128:131], v[160:163], v[60:63]
	v_mfma_f32_16x16x32_bf16 v[56:59], v[136:139], v[160:163], v[56:59]
	v_mfma_f32_16x16x32_bf16 v[44:47], v[128:131], v[168:171], v[44:47]
	v_mfma_f32_16x16x32_bf16 v[40:43], v[136:139], v[168:171], v[40:43]
	v_mfma_f32_16x16x32_bf16 v[28:31], v[128:131], v[192:195], v[28:31]
	v_mfma_f32_16x16x32_bf16 v[24:27], v[136:139], v[192:195], v[24:27]
	v_mfma_f32_16x16x32_bf16 v[12:15], v[128:131], v[200:203], v[12:15]
	v_mfma_f32_16x16x32_bf16 v[8:11], v[136:139], v[200:203], v[8:11]
	v_mfma_f32_16x16x32_bf16 v[60:63], v[132:135], v[164:167], v[60:63]
	v_mfma_f32_16x16x32_bf16 v[56:59], v[140:143], v[164:167], v[56:59]
	v_mfma_f32_16x16x32_bf16 v[44:47], v[132:135], v[172:175], v[44:47]
	v_mfma_f32_16x16x32_bf16 v[40:43], v[140:143], v[172:175], v[40:43]
	v_mfma_f32_16x16x32_bf16 v[28:31], v[132:135], v[196:199], v[28:31]
	v_mfma_f32_16x16x32_bf16 v[24:27], v[140:143], v[196:199], v[24:27]
	v_mfma_f32_16x16x32_bf16 v[12:15], v[132:135], v[204:207], v[12:15]
	v_mfma_f32_16x16x32_bf16 v[8:11], v[140:143], v[204:207], v[8:11]
	s_setprio 0
	s_setprio 1
	v_mfma_f32_16x16x32_bf16 v[52:55], v[144:147], v[160:163], v[52:55]
	v_mfma_f32_16x16x32_bf16 v[48:51], v[152:155], v[160:163], v[48:51]
	v_mfma_f32_16x16x32_bf16 v[36:39], v[144:147], v[168:171], v[36:39]
	v_mfma_f32_16x16x32_bf16 v[32:35], v[152:155], v[168:171], v[32:35]
	v_mfma_f32_16x16x32_bf16 v[20:23], v[144:147], v[192:195], v[20:23]
	v_mfma_f32_16x16x32_bf16 v[16:19], v[152:155], v[192:195], v[16:19]
	v_mfma_f32_16x16x32_bf16 v[4:7], v[144:147], v[200:203], v[4:7]
	v_mfma_f32_16x16x32_bf16 v[0:3], v[152:155], v[200:203], v[0:3]
	v_mfma_f32_16x16x32_bf16 v[52:55], v[148:151], v[164:167], v[52:55]
	v_mfma_f32_16x16x32_bf16 v[48:51], v[156:159], v[164:167], v[48:51]
	v_mfma_f32_16x16x32_bf16 v[36:39], v[148:151], v[172:175], v[36:39]
	v_mfma_f32_16x16x32_bf16 v[32:35], v[156:159], v[172:175], v[32:35]
	v_mfma_f32_16x16x32_bf16 v[20:23], v[148:151], v[196:199], v[20:23]
	v_mfma_f32_16x16x32_bf16 v[16:19], v[156:159], v[196:199], v[16:19]
	v_mfma_f32_16x16x32_bf16 v[4:7], v[148:151], v[204:207], v[4:7]
	v_mfma_f32_16x16x32_bf16 v[0:3], v[156:159], v[204:207], v[0:3]
	s_barrier
	s_setprio 0
	s_add_i32 s58, s58, 2
	s_add_u32 s42, s42, 0x100
	s_addc_u32 s43, s43, 0
	s_add_u32 s25, s25, 0x100
	s_addc_u32 s35, s35, 0
	s_cmp_gt_u32 s58, 29
	s_cbranch_scc0 .LBB0_543
	s_and_b64 vcc, exec, s[22:23]
	s_cbranch_vccz .LBB0_546
	s_barrier

.LBB0_635:
	s_ashr_i32 s67, s66, 31
	s_lshl_b64 s[12:13], s[66:67], 20
	s_add_u32 s70, s55, s12
	s_addc_u32 s71, s57, s13
	s_and_b64 s[6:7], s[6:7], exec
	s_cselect_b32 s1, s71, s11
	s_cselect_b32 s3, s70, s10
	s_add_u32 s6, s8, 0x80080
	s_addc_u32 s7, s9, 0
	s_add_u32 s12, s10, 0x100
	s_addc_u32 s13, s11, 0
	s_mov_b32 s15, -2
	s_waitcnt vmcnt(0)
	ds_read_b128 v[148:151], v197
	ds_read_b128 v[170:173], v197 offset:1024
	ds_read_b128 v[174:177], v197 offset:2048
	ds_read_b128 v[178:181], v197 offset:3072
	ds_read_b128 v[182:185], v198
	ds_read_b128 v[186:189], v198 offset:1024
	ds_read_b128 v[202:205], v198 offset:2048
	ds_read_b128 v[206:209], v198 offset:3072
	s_add_u32 s8, s6, 0xfff80080
	s_addc_u32 s9, s7, -1
	s_cmp_eq_u32 s15, 28
	s_cselect_b32 s11, s69, s9
	s_cselect_b32 s10, s68, s8
	s_cselect_b32 s9, s1, s13
	s_cselect_b32 s8, s3, s12
	s_add_i32 m0, s72, 0xc000
	ds_read_b128 v[214:217], v199
	ds_read_b128 v[218:221], v199 offset:1024
	ds_read_b128 v[222:225], v199 offset:2048
	ds_read_b128 v[226:229], v199 offset:3072
	ds_read_b128 v[230:233], v199 offset:4096
	ds_read_b128 v[234:237], v199 offset:5120
	ds_read_b128 v[238:241], v199 offset:6144
	global_load_lds_dwordx4 v162, s[6:7]
	s_add_i32 m0, s72, 0xe000
	ds_read_b128 v[242:245], v199 offset:7168
	global_load_lds_dwordx4 v164, s[6:7]
	s_waitcnt vmcnt(8)
	s_waitcnt lgkmcnt(0)
	s_setprio 1
	s_barrier
	v_mfma_f32_16x16x32_bf16 v[112:115], v[148:151], v[214:217], 0
	v_mfma_f32_16x16x32_bf16 v[80:83], v[174:177], v[214:217], 0
	v_mfma_f32_16x16x32_bf16 v[116:119], v[148:151], v[222:225], 0
	v_mfma_f32_16x16x32_bf16 v[88:91], v[174:177], v[222:225], 0
	v_mfma_f32_16x16x32_bf16 v[124:127], v[148:151], v[230:233], 0
	v_mfma_f32_16x16x32_bf16 v[92:95], v[174:177], v[230:233], 0
	v_mfma_f32_16x16x32_bf16 v[120:123], v[148:151], v[238:241], 0
	v_mfma_f32_16x16x32_bf16 v[84:87], v[174:177], v[238:241], 0
	v_mfma_f32_16x16x32_bf16 v[112:115], v[170:173], v[218:221], v[112:115]
	v_mfma_f32_16x16x32_bf16 v[80:83], v[178:181], v[218:221], v[80:83]
	v_mfma_f32_16x16x32_bf16 v[116:119], v[170:173], v[226:229], v[116:119]
	v_mfma_f32_16x16x32_bf16 v[88:91], v[178:181], v[226:229], v[88:91]
	v_mfma_f32_16x16x32_bf16 v[124:127], v[170:173], v[234:237], v[124:127]
	v_mfma_f32_16x16x32_bf16 v[92:95], v[178:181], v[234:237], v[92:95]
	v_mfma_f32_16x16x32_bf16 v[120:123], v[170:173], v[242:245], v[120:123]
	v_mfma_f32_16x16x32_bf16 v[84:87], v[178:181], v[242:245], v[84:87]
	s_setprio 0
	s_setprio 1
	v_mfma_f32_16x16x32_bf16 v[108:111], v[182:185], v[214:217], 0
	v_mfma_f32_16x16x32_bf16 v[76:79], v[202:205], v[214:217], 0
	v_mfma_f32_16x16x32_bf16 v[104:107], v[182:185], v[222:225], 0
	v_mfma_f32_16x16x32_bf16 v[72:75], v[202:205], v[222:225], 0
	v_mfma_f32_16x16x32_bf16 v[100:103], v[182:185], v[230:233], 0
	v_mfma_f32_16x16x32_bf16 v[68:71], v[202:205], v[230:233], 0
	v_mfma_f32_16x16x32_bf16 v[96:99], v[182:185], v[238:241], 0
	v_mfma_f32_16x16x32_bf16 v[64:67], v[202:205], v[238:241], 0
	v_mfma_f32_16x16x32_bf16 v[108:111], v[186:189], v[218:221], v[108:111]
	v_mfma_f32_16x16x32_bf16 v[76:79], v[206:209], v[218:221], v[76:79]
	v_mfma_f32_16x16x32_bf16 v[104:107], v[186:189], v[226:229], v[104:107]
	v_mfma_f32_16x16x32_bf16 v[72:75], v[206:209], v[226:229], v[72:75]
	v_mfma_f32_16x16x32_bf16 v[100:103], v[186:189], v[234:237], v[100:103]
	v_mfma_f32_16x16x32_bf16 v[68:71], v[206:209], v[234:237], v[68:71]
	v_mfma_f32_16x16x32_bf16 v[96:99], v[186:189], v[242:245], v[96:99]
	v_mfma_f32_16x16x32_bf16 v[64:67], v[206:209], v[242:245], v[64:67]
	s_barrier
	s_setprio 0
	s_add_i32 s16, s94, s63
	s_add_u32 s98, s8, s40
	s_addc_u32 s99, s9, s41
	s_mov_b32 m0, s16
	ds_read_b128 v[214:217], v199 offset:16384
	ds_read_b128 v[218:221], v199 offset:17408
	ds_read_b128 v[222:225], v199 offset:18432
	ds_read_b128 v[226:229], v199 offset:19456
	ds_read_b128 v[230:233], v199 offset:20480
	global_load_lds_dwordx4 v154, s[8:9]
	s_add_i32 m0, s16, 0x2000
	s_add_u32 s16, s8, 0x80000
	s_addc_u32 s17, s9, 0
	s_add_i32 s18, s95, s63
	global_load_lds_dwordx4 v158, s[8:9]
	s_mov_b32 m0, s18
	s_add_u32 s100, s10, s40
	s_addc_u32 s101, s11, s41
	global_load_lds_dwordx4 v154, s[16:17]
	s_add_i32 m0, s18, 0x2000
	ds_read_b128 v[242:245], v199 offset:23552
	global_load_lds_dwordx4 v158, s[16:17]
	s_mov_b32 m0, s72
	ds_read_b128 v[238:241], v199 offset:22528
	global_load_lds_dwordx4 v152, s[10:11]
	s_mov_b32 m0, s73
	ds_read_b128 v[234:237], v199 offset:21504
	global_load_lds_dwordx4 v156, s[10:11]
	s_waitcnt vmcnt(8)
	s_waitcnt lgkmcnt(0)
	s_setprio 1
	s_barrier
	v_mfma_f32_16x16x32_bf16 v[48:51], v[148:151], v[214:217], 0
	v_mfma_f32_16x16x32_bf16 v[16:19], v[174:177], v[214:217], 0
	v_mfma_f32_16x16x32_bf16 v[52:55], v[148:151], v[222:225], 0
	v_mfma_f32_16x16x32_bf16 v[24:27], v[174:177], v[222:225], 0
	v_mfma_f32_16x16x32_bf16 v[60:63], v[148:151], v[230:233], 0
	v_mfma_f32_16x16x32_bf16 v[28:31], v[174:177], v[230:233], 0
	v_mfma_f32_16x16x32_bf16 v[56:59], v[148:151], v[238:241], 0
	v_mfma_f32_16x16x32_bf16 v[20:23], v[174:177], v[238:241], 0
	v_mfma_f32_16x16x32_bf16 v[48:51], v[170:173], v[218:221], v[48:51]
	v_mfma_f32_16x16x32_bf16 v[16:19], v[178:181], v[218:221], v[16:19]
	v_mfma_f32_16x16x32_bf16 v[52:55], v[170:173], v[226:229], v[52:55]
	v_mfma_f32_16x16x32_bf16 v[24:27], v[178:181], v[226:229], v[24:27]
	v_mfma_f32_16x16x32_bf16 v[60:63], v[170:173], v[234:237], v[60:63]
	v_mfma_f32_16x16x32_bf16 v[28:31], v[178:181], v[234:237], v[28:31]
	v_mfma_f32_16x16x32_bf16 v[56:59], v[170:173], v[242:245], v[56:59]
	v_mfma_f32_16x16x32_bf16 v[20:23], v[178:181], v[242:245], v[20:23]
	s_setprio 0
	s_setprio 1
	v_mfma_f32_16x16x32_bf16 v[44:47], v[182:185], v[214:217], 0
	v_mfma_f32_16x16x32_bf16 v[12:15], v[202:205], v[214:217], 0
	v_mfma_f32_16x16x32_bf16 v[40:43], v[182:185], v[222:225], 0
	v_mfma_f32_16x16x32_bf16 v[8:11], v[202:205], v[222:225], 0
	v_mfma_f32_16x16x32_bf16 v[36:39], v[182:185], v[230:233], 0
	v_mfma_f32_16x16x32_bf16 v[4:7], v[202:205], v[230:233], 0
	v_mfma_f32_16x16x32_bf16 v[32:35], v[182:185], v[238:241], 0
	v_mfma_f32_16x16x32_bf16 v[0:3], v[202:205], v[238:241], 0
	v_mfma_f32_16x16x32_bf16 v[44:47], v[186:189], v[218:221], v[44:47]
	v_mfma_f32_16x16x32_bf16 v[12:15], v[206:209], v[218:221], v[12:15]
	v_mfma_f32_16x16x32_bf16 v[40:43], v[186:189], v[226:229], v[40:43]
	v_mfma_f32_16x16x32_bf16 v[8:11], v[206:209], v[226:229], v[8:11]
	v_mfma_f32_16x16x32_bf16 v[36:39], v[186:189], v[234:237], v[36:39]
	v_mfma_f32_16x16x32_bf16 v[4:7], v[206:209], v[234:237], v[4:7]
	v_mfma_f32_16x16x32_bf16 v[32:35], v[186:189], v[242:245], v[32:35]
	v_mfma_f32_16x16x32_bf16 v[0:3], v[206:209], v[242:245], v[0:3]
	s_barrier
	s_setprio 0
	s_add_i32 s16, 0, 0x18000
	s_add_i32 s17, 0, 0x1c000
	v_add_u32_e32 v178, s16, v196
	v_add_u32_e32 v201, s17, v196
	ds_read_b128 v[148:151], v178
	ds_read_b128 v[170:173], v178 offset:1024
	ds_read_b128 v[174:177], v178 offset:2048
	ds_read_b128 v[178:181], v178 offset:3072
	ds_read_b128 v[182:185], v201
	ds_read_b128 v[186:189], v201 offset:1024
	ds_read_b128 v[202:205], v201 offset:2048
	ds_read_b128 v[206:209], v201 offset:3072
	s_add_u32 s10, s10, 0x80000
	s_addc_u32 s11, s11, 0
	s_mov_b32 m0, s74
	ds_read_b128 v[214:217], v199 offset:32768
	ds_read_b128 v[218:221], v199 offset:33792
	ds_read_b128 v[222:225], v199 offset:34816
	ds_read_b128 v[226:229], v199 offset:35840
	ds_read_b128 v[230:233], v199 offset:36864
	ds_read_b128 v[234:237], v199 offset:37888
	ds_read_b128 v[238:241], v199 offset:38912
	global_load_lds_dwordx4 v152, s[10:11]
	s_mov_b32 m0, s75
	ds_read_b128 v[242:245], v199 offset:39936
	global_load_lds_dwordx4 v156, s[10:11]
	s_waitcnt vmcnt(8)
	s_waitcnt lgkmcnt(0)
	s_setprio 1
	s_barrier
	v_mfma_f32_16x16x32_bf16 v[112:115], v[148:151], v[214:217], v[112:115]
	v_mfma_f32_16x16x32_bf16 v[80:83], v[174:177], v[214:217], v[80:83]
	v_mfma_f32_16x16x32_bf16 v[116:119], v[148:151], v[222:225], v[116:119]
	v_mfma_f32_16x16x32_bf16 v[88:91], v[174:177], v[222:225], v[88:91]
	v_mfma_f32_16x16x32_bf16 v[124:127], v[148:151], v[230:233], v[124:127]
	v_mfma_f32_16x16x32_bf16 v[92:95], v[174:177], v[230:233], v[92:95]
	v_mfma_f32_16x16x32_bf16 v[120:123], v[148:151], v[238:241], v[120:123]
	v_mfma_f32_16x16x32_bf16 v[84:87], v[174:177], v[238:241], v[84:87]
	v_mfma_f32_16x16x32_bf16 v[112:115], v[170:173], v[218:221], v[112:115]
	v_mfma_f32_16x16x32_bf16 v[80:83], v[178:181], v[218:221], v[80:83]
	v_mfma_f32_16x16x32_bf16 v[116:119], v[170:173], v[226:229], v[116:119]
	v_mfma_f32_16x16x32_bf16 v[88:91], v[178:181], v[226:229], v[88:91]
	v_mfma_f32_16x16x32_bf16 v[124:127], v[170:173], v[234:237], v[124:127]
	v_mfma_f32_16x16x32_bf16 v[92:95], v[178:181], v[234:237], v[92:95]
	v_mfma_f32_16x16x32_bf16 v[120:123], v[170:173], v[242:245], v[120:123]
	v_mfma_f32_16x16x32_bf16 v[84:87], v[178:181], v[242:245], v[84:87]
	s_setprio 0
	s_setprio 1
	v_mfma_f32_16x16x32_bf16 v[108:111], v[182:185], v[214:217], v[108:111]
	v_mfma_f32_16x16x32_bf16 v[76:79], v[202:205], v[214:217], v[76:79]
	v_mfma_f32_16x16x32_bf16 v[104:107], v[182:185], v[222:225], v[104:107]
	v_mfma_f32_16x16x32_bf16 v[72:75], v[202:205], v[222:225], v[72:75]
	v_mfma_f32_16x16x32_bf16 v[100:103], v[182:185], v[230:233], v[100:103]
	v_mfma_f32_16x16x32_bf16 v[68:71], v[202:205], v[230:233], v[68:71]
	v_mfma_f32_16x16x32_bf16 v[96:99], v[182:185], v[238:241], v[96:99]
	v_mfma_f32_16x16x32_bf16 v[64:67], v[202:205], v[238:241], v[64:67]
	v_mfma_f32_16x16x32_bf16 v[108:111], v[186:189], v[218:221], v[108:111]
	v_mfma_f32_16x16x32_bf16 v[76:79], v[206:209], v[218:221], v[76:79]
	v_mfma_f32_16x16x32_bf16 v[104:107], v[186:189], v[226:229], v[104:107]
	v_mfma_f32_16x16x32_bf16 v[72:75], v[206:209], v[226:229], v[72:75]
	v_mfma_f32_16x16x32_bf16 v[100:103], v[186:189], v[234:237], v[100:103]
	v_mfma_f32_16x16x32_bf16 v[68:71], v[206:209], v[234:237], v[68:71]
	v_mfma_f32_16x16x32_bf16 v[96:99], v[186:189], v[242:245], v[96:99]
	v_mfma_f32_16x16x32_bf16 v[64:67], v[206:209], v[242:245], v[64:67]
	s_barrier
	s_setprio 0
	s_add_i32 s10, s16, s63
	s_mov_b32 m0, s10
	ds_read_b128 v[214:217], v199 offset:49152
	ds_read_b128 v[218:221], v199 offset:50176
	ds_read_b128 v[222:225], v199 offset:51200
	ds_read_b128 v[226:229], v199 offset:52224
	global_load_lds_dwordx4 v154, s[98:99]
	s_add_i32 m0, s10, 0x2000
	s_add_u32 s8, s8, 0x80080
	s_addc_u32 s9, s9, 0
	s_add_i32 s10, s17, s63
	global_load_lds_dwordx4 v158, s[98:99]
	s_mov_b32 m0, s10
	ds_read_b128 v[242:245], v199 offset:56320
	global_load_lds_dwordx4 v154, s[8:9]
	s_add_i32 m0, s10, 0x2000
	ds_read_b128 v[238:241], v199 offset:55296
	global_load_lds_dwordx4 v158, s[8:9]
	s_mov_b32 m0, s82
	ds_read_b128 v[234:237], v199 offset:54272
	global_load_lds_dwordx4 v152, s[100:101]
	s_mov_b32 m0, s83
	ds_read_b128 v[230:233], v199 offset:53248
	global_load_lds_dwordx4 v156, s[100:101]
	s_waitcnt vmcnt(8)
	s_waitcnt lgkmcnt(0)
	s_setprio 1
	s_barrier
	v_mfma_f32_16x16x32_bf16 v[48:51], v[148:151], v[214:217], v[48:51]
	v_mfma_f32_16x16x32_bf16 v[16:19], v[174:177], v[214:217], v[16:19]
	v_mfma_f32_16x16x32_bf16 v[52:55], v[148:151], v[222:225], v[52:55]
	v_mfma_f32_16x16x32_bf16 v[24:27], v[174:177], v[222:225], v[24:27]
	v_mfma_f32_16x16x32_bf16 v[60:63], v[148:151], v[230:233], v[60:63]
	v_mfma_f32_16x16x32_bf16 v[28:31], v[174:177], v[230:233], v[28:31]
	v_mfma_f32_16x16x32_bf16 v[56:59], v[148:151], v[238:241], v[56:59]
	v_mfma_f32_16x16x32_bf16 v[20:23], v[174:177], v[238:241], v[20:23]
	v_mfma_f32_16x16x32_bf16 v[48:51], v[170:173], v[218:221], v[48:51]
	v_mfma_f32_16x16x32_bf16 v[16:19], v[178:181], v[218:221], v[16:19]
	v_mfma_f32_16x16x32_bf16 v[52:55], v[170:173], v[226:229], v[52:55]
	v_mfma_f32_16x16x32_bf16 v[24:27], v[178:181], v[226:229], v[24:27]
	v_mfma_f32_16x16x32_bf16 v[60:63], v[170:173], v[234:237], v[60:63]
	v_mfma_f32_16x16x32_bf16 v[28:31], v[178:181], v[234:237], v[28:31]
	v_mfma_f32_16x16x32_bf16 v[56:59], v[170:173], v[242:245], v[56:59]
	v_mfma_f32_16x16x32_bf16 v[20:23], v[178:181], v[242:245], v[20:23]
	s_setprio 0
	s_setprio 1
	v_mfma_f32_16x16x32_bf16 v[44:47], v[182:185], v[214:217], v[44:47]
	v_mfma_f32_16x16x32_bf16 v[12:15], v[202:205], v[214:217], v[12:15]
	v_mfma_f32_16x16x32_bf16 v[40:43], v[182:185], v[222:225], v[40:43]
	v_mfma_f32_16x16x32_bf16 v[8:11], v[202:205], v[222:225], v[8:11]
	v_mfma_f32_16x16x32_bf16 v[36:39], v[182:185], v[230:233], v[36:39]
	v_mfma_f32_16x16x32_bf16 v[4:7], v[202:205], v[230:233], v[4:7]
	v_mfma_f32_16x16x32_bf16 v[32:35], v[182:185], v[238:241], v[32:35]
	v_mfma_f32_16x16x32_bf16 v[0:3], v[202:205], v[238:241], v[0:3]
	v_mfma_f32_16x16x32_bf16 v[44:47], v[186:189], v[218:221], v[44:47]
	v_mfma_f32_16x16x32_bf16 v[12:15], v[206:209], v[218:221], v[12:15]
	v_mfma_f32_16x16x32_bf16 v[40:43], v[186:189], v[226:229], v[40:43]
	v_mfma_f32_16x16x32_bf16 v[8:11], v[206:209], v[226:229], v[8:11]
	v_mfma_f32_16x16x32_bf16 v[36:39], v[186:189], v[234:237], v[36:39]
	v_mfma_f32_16x16x32_bf16 v[4:7], v[206:209], v[234:237], v[4:7]
	v_mfma_f32_16x16x32_bf16 v[32:35], v[186:189], v[242:245], v[32:35]
	v_mfma_f32_16x16x32_bf16 v[0:3], v[206:209], v[242:245], v[0:3]
	s_barrier
	s_setprio 0
	s_add_i32 s15, s15, 2
	s_add_u32 s6, s6, 0x100
	s_addc_u32 s7, s7, 0
	s_add_u32 s12, s12, 0x100
	s_addc_u32 s13, s13, 0
	s_cmp_gt_u32 s15, 29
.LBB0_636:
	ds_read_b128 v[148:151], v197
	ds_read_b128 v[170:173], v197 offset:1024
	ds_read_b128 v[174:177], v197 offset:2048
	ds_read_b128 v[178:181], v197 offset:3072
	ds_read_b128 v[182:185], v198
	ds_read_b128 v[186:189], v198 offset:1024
	ds_read_b128 v[202:205], v198 offset:2048
	ds_read_b128 v[206:209], v198 offset:3072
	s_add_u32 s8, s6, 0xfff80080
	s_addc_u32 s9, s7, -1
	s_cmp_eq_u32 s15, 28
	s_cselect_b32 s11, s69, s9
	s_cselect_b32 s10, s68, s8
	s_cselect_b32 s9, s1, s13
	s_cselect_b32 s8, s3, s12
	s_add_i32 m0, s72, 0xc000
	ds_read_b128 v[214:217], v199
	ds_read_b128 v[218:221], v199 offset:1024
	ds_read_b128 v[222:225], v199 offset:2048
	ds_read_b128 v[226:229], v199 offset:3072
	ds_read_b128 v[230:233], v199 offset:4096
	ds_read_b128 v[234:237], v199 offset:5120
	ds_read_b128 v[238:241], v199 offset:6144
	global_load_lds_dwordx4 v162, s[6:7]
	s_add_i32 m0, s72, 0xe000
	ds_read_b128 v[242:245], v199 offset:7168
	global_load_lds_dwordx4 v164, s[6:7]
	s_waitcnt vmcnt(8)
	s_waitcnt lgkmcnt(0)
	s_setprio 1
	s_barrier
	v_mfma_f32_16x16x32_bf16 v[112:115], v[148:151], v[214:217], v[112:115]
	v_mfma_f32_16x16x32_bf16 v[80:83], v[174:177], v[214:217], v[80:83]
	v_mfma_f32_16x16x32_bf16 v[116:119], v[148:151], v[222:225], v[116:119]
	v_mfma_f32_16x16x32_bf16 v[88:91], v[174:177], v[222:225], v[88:91]
	v_mfma_f32_16x16x32_bf16 v[124:127], v[148:151], v[230:233], v[124:127]
	v_mfma_f32_16x16x32_bf16 v[92:95], v[174:177], v[230:233], v[92:95]
	v_mfma_f32_16x16x32_bf16 v[120:123], v[148:151], v[238:241], v[120:123]
	v_mfma_f32_16x16x32_bf16 v[84:87], v[174:177], v[238:241], v[84:87]
	v_mfma_f32_16x16x32_bf16 v[112:115], v[170:173], v[218:221], v[112:115]
	v_mfma_f32_16x16x32_bf16 v[80:83], v[178:181], v[218:221], v[80:83]
	v_mfma_f32_16x16x32_bf16 v[116:119], v[170:173], v[226:229], v[116:119]
	v_mfma_f32_16x16x32_bf16 v[88:91], v[178:181], v[226:229], v[88:91]
	v_mfma_f32_16x16x32_bf16 v[124:127], v[170:173], v[234:237], v[124:127]
	v_mfma_f32_16x16x32_bf16 v[92:95], v[178:181], v[234:237], v[92:95]
	v_mfma_f32_16x16x32_bf16 v[120:123], v[170:173], v[242:245], v[120:123]
	v_mfma_f32_16x16x32_bf16 v[84:87], v[178:181], v[242:245], v[84:87]
	s_setprio 0
	s_setprio 1
	v_mfma_f32_16x16x32_bf16 v[108:111], v[182:185], v[214:217], v[108:111]
	v_mfma_f32_16x16x32_bf16 v[76:79], v[202:205], v[214:217], v[76:79]
	v_mfma_f32_16x16x32_bf16 v[104:107], v[182:185], v[222:225], v[104:107]
	v_mfma_f32_16x16x32_bf16 v[72:75], v[202:205], v[222:225], v[72:75]
	v_mfma_f32_16x16x32_bf16 v[100:103], v[182:185], v[230:233], v[100:103]
	v_mfma_f32_16x16x32_bf16 v[68:71], v[202:205], v[230:233], v[68:71]
	v_mfma_f32_16x16x32_bf16 v[96:99], v[182:185], v[238:241], v[96:99]
	v_mfma_f32_16x16x32_bf16 v[64:67], v[202:205], v[238:241], v[64:67]
	v_mfma_f32_16x16x32_bf16 v[108:111], v[186:189], v[218:221], v[108:111]
	v_mfma_f32_16x16x32_bf16 v[76:79], v[206:209], v[218:221], v[76:79]
	v_mfma_f32_16x16x32_bf16 v[104:107], v[186:189], v[226:229], v[104:107]
	v_mfma_f32_16x16x32_bf16 v[72:75], v[206:209], v[226:229], v[72:75]
	v_mfma_f32_16x16x32_bf16 v[100:103], v[186:189], v[234:237], v[100:103]
	v_mfma_f32_16x16x32_bf16 v[68:71], v[206:209], v[234:237], v[68:71]
	v_mfma_f32_16x16x32_bf16 v[96:99], v[186:189], v[242:245], v[96:99]
	v_mfma_f32_16x16x32_bf16 v[64:67], v[206:209], v[242:245], v[64:67]
	s_barrier
	s_setprio 0
	s_add_i32 s16, s94, s63
	s_add_u32 s98, s8, s40
	s_addc_u32 s99, s9, s41
	s_mov_b32 m0, s16
	ds_read_b128 v[214:217], v199 offset:16384
	ds_read_b128 v[218:221], v199 offset:17408
	ds_read_b128 v[222:225], v199 offset:18432
	ds_read_b128 v[226:229], v199 offset:19456
	ds_read_b128 v[230:233], v199 offset:20480
	global_load_lds_dwordx4 v154, s[8:9]
	s_add_i32 m0, s16, 0x2000
	s_add_u32 s16, s8, 0x80000
	s_addc_u32 s17, s9, 0
	s_add_i32 s18, s95, s63
	global_load_lds_dwordx4 v158, s[8:9]
	s_mov_b32 m0, s18
	s_add_u32 s100, s10, s40
	s_addc_u32 s101, s11, s41
	global_load_lds_dwordx4 v154, s[16:17]
	s_add_i32 m0, s18, 0x2000
	ds_read_b128 v[242:245], v199 offset:23552
	global_load_lds_dwordx4 v158, s[16:17]
	s_mov_b32 m0, s72
	ds_read_b128 v[238:241], v199 offset:22528
	global_load_lds_dwordx4 v152, s[10:11]
	s_mov_b32 m0, s73
	ds_read_b128 v[234:237], v199 offset:21504
	global_load_lds_dwordx4 v156, s[10:11]
	s_waitcnt vmcnt(8)
	s_waitcnt lgkmcnt(0)
	s_setprio 1
	s_barrier
	v_mfma_f32_16x16x32_bf16 v[48:51], v[148:151], v[214:217], v[48:51]
	v_mfma_f32_16x16x32_bf16 v[16:19], v[174:177], v[214:217], v[16:19]
	v_mfma_f32_16x16x32_bf16 v[52:55], v[148:151], v[222:225], v[52:55]
	v_mfma_f32_16x16x32_bf16 v[24:27], v[174:177], v[222:225], v[24:27]
	v_mfma_f32_16x16x32_bf16 v[60:63], v[148:151], v[230:233], v[60:63]
	v_mfma_f32_16x16x32_bf16 v[28:31], v[174:177], v[230:233], v[28:31]
	v_mfma_f32_16x16x32_bf16 v[56:59], v[148:151], v[238:241], v[56:59]
	v_mfma_f32_16x16x32_bf16 v[20:23], v[174:177], v[238:241], v[20:23]
	v_mfma_f32_16x16x32_bf16 v[48:51], v[170:173], v[218:221], v[48:51]
	v_mfma_f32_16x16x32_bf16 v[16:19], v[178:181], v[218:221], v[16:19]
	v_mfma_f32_16x16x32_bf16 v[52:55], v[170:173], v[226:229], v[52:55]
	v_mfma_f32_16x16x32_bf16 v[24:27], v[178:181], v[226:229], v[24:27]
	v_mfma_f32_16x16x32_bf16 v[60:63], v[170:173], v[234:237], v[60:63]
	v_mfma_f32_16x16x32_bf16 v[28:31], v[178:181], v[234:237], v[28:31]
	v_mfma_f32_16x16x32_bf16 v[56:59], v[170:173], v[242:245], v[56:59]
	v_mfma_f32_16x16x32_bf16 v[20:23], v[178:181], v[242:245], v[20:23]
	s_setprio 0
	s_setprio 1
	v_mfma_f32_16x16x32_bf16 v[44:47], v[182:185], v[214:217], v[44:47]
	v_mfma_f32_16x16x32_bf16 v[12:15], v[202:205], v[214:217], v[12:15]
	v_mfma_f32_16x16x32_bf16 v[40:43], v[182:185], v[222:225], v[40:43]
	v_mfma_f32_16x16x32_bf16 v[8:11], v[202:205], v[222:225], v[8:11]
	v_mfma_f32_16x16x32_bf16 v[36:39], v[182:185], v[230:233], v[36:39]
	v_mfma_f32_16x16x32_bf16 v[4:7], v[202:205], v[230:233], v[4:7]
	v_mfma_f32_16x16x32_bf16 v[32:35], v[182:185], v[238:241], v[32:35]
	v_mfma_f32_16x16x32_bf16 v[0:3], v[202:205], v[238:241], v[0:3]
	v_mfma_f32_16x16x32_bf16 v[44:47], v[186:189], v[218:221], v[44:47]
	v_mfma_f32_16x16x32_bf16 v[12:15], v[206:209], v[218:221], v[12:15]
	v_mfma_f32_16x16x32_bf16 v[40:43], v[186:189], v[226:229], v[40:43]
	v_mfma_f32_16x16x32_bf16 v[8:11], v[206:209], v[226:229], v[8:11]
	v_mfma_f32_16x16x32_bf16 v[36:39], v[186:189], v[234:237], v[36:39]
	v_mfma_f32_16x16x32_bf16 v[4:7], v[206:209], v[234:237], v[4:7]
	v_mfma_f32_16x16x32_bf16 v[32:35], v[186:189], v[242:245], v[32:35]
	v_mfma_f32_16x16x32_bf16 v[0:3], v[206:209], v[242:245], v[0:3]
	s_barrier
	s_setprio 0
	s_add_i32 s16, 0, 0x18000
	s_add_i32 s17, 0, 0x1c000
	v_add_u32_e32 v178, s16, v196
	v_add_u32_e32 v201, s17, v196
	ds_read_b128 v[148:151], v178
	ds_read_b128 v[170:173], v178 offset:1024
	ds_read_b128 v[174:177], v178 offset:2048
	ds_read_b128 v[178:181], v178 offset:3072
	ds_read_b128 v[182:185], v201
	ds_read_b128 v[186:189], v201 offset:1024
	ds_read_b128 v[202:205], v201 offset:2048
	ds_read_b128 v[206:209], v201 offset:3072
	s_add_u32 s10, s10, 0x80000
	s_addc_u32 s11, s11, 0
	s_mov_b32 m0, s74
	ds_read_b128 v[214:217], v199 offset:32768
	ds_read_b128 v[218:221], v199 offset:33792
	ds_read_b128 v[222:225], v199 offset:34816
	ds_read_b128 v[226:229], v199 offset:35840
	ds_read_b128 v[230:233], v199 offset:36864
	ds_read_b128 v[234:237], v199 offset:37888
	ds_read_b128 v[238:241], v199 offset:38912
	global_load_lds_dwordx4 v152, s[10:11]
	s_mov_b32 m0, s75
	ds_read_b128 v[242:245], v199 offset:39936
	global_load_lds_dwordx4 v156, s[10:11]
	s_waitcnt vmcnt(8)
	s_waitcnt lgkmcnt(0)
	s_setprio 1
	s_barrier
	v_mfma_f32_16x16x32_bf16 v[112:115], v[148:151], v[214:217], v[112:115]
	v_mfma_f32_16x16x32_bf16 v[80:83], v[174:177], v[214:217], v[80:83]
	v_mfma_f32_16x16x32_bf16 v[116:119], v[148:151], v[222:225], v[116:119]
	v_mfma_f32_16x16x32_bf16 v[88:91], v[174:177], v[222:225], v[88:91]
	v_mfma_f32_16x16x32_bf16 v[124:127], v[148:151], v[230:233], v[124:127]
	v_mfma_f32_16x16x32_bf16 v[92:95], v[174:177], v[230:233], v[92:95]
	v_mfma_f32_16x16x32_bf16 v[120:123], v[148:151], v[238:241], v[120:123]
	v_mfma_f32_16x16x32_bf16 v[84:87], v[174:177], v[238:241], v[84:87]
	v_mfma_f32_16x16x32_bf16 v[112:115], v[170:173], v[218:221], v[112:115]
	v_mfma_f32_16x16x32_bf16 v[80:83], v[178:181], v[218:221], v[80:83]
	v_mfma_f32_16x16x32_bf16 v[116:119], v[170:173], v[226:229], v[116:119]
	v_mfma_f32_16x16x32_bf16 v[88:91], v[178:181], v[226:229], v[88:91]
	v_mfma_f32_16x16x32_bf16 v[124:127], v[170:173], v[234:237], v[124:127]
	v_mfma_f32_16x16x32_bf16 v[92:95], v[178:181], v[234:237], v[92:95]
	v_mfma_f32_16x16x32_bf16 v[120:123], v[170:173], v[242:245], v[120:123]
	v_mfma_f32_16x16x32_bf16 v[84:87], v[178:181], v[242:245], v[84:87]
	s_setprio 0
	s_setprio 1
	v_mfma_f32_16x16x32_bf16 v[108:111], v[182:185], v[214:217], v[108:111]
	v_mfma_f32_16x16x32_bf16 v[76:79], v[202:205], v[214:217], v[76:79]
	v_mfma_f32_16x16x32_bf16 v[104:107], v[182:185], v[222:225], v[104:107]
	v_mfma_f32_16x16x32_bf16 v[72:75], v[202:205], v[222:225], v[72:75]
	v_mfma_f32_16x16x32_bf16 v[100:103], v[182:185], v[230:233], v[100:103]
	v_mfma_f32_16x16x32_bf16 v[68:71], v[202:205], v[230:233], v[68:71]
	v_mfma_f32_16x16x32_bf16 v[96:99], v[182:185], v[238:241], v[96:99]
	v_mfma_f32_16x16x32_bf16 v[64:67], v[202:205], v[238:241], v[64:67]
	v_mfma_f32_16x16x32_bf16 v[108:111], v[186:189], v[218:221], v[108:111]
	v_mfma_f32_16x16x32_bf16 v[76:79], v[206:209], v[218:221], v[76:79]
	v_mfma_f32_16x16x32_bf16 v[104:107], v[186:189], v[226:229], v[104:107]
	v_mfma_f32_16x16x32_bf16 v[72:75], v[206:209], v[226:229], v[72:75]
	v_mfma_f32_16x16x32_bf16 v[100:103], v[186:189], v[234:237], v[100:103]
	v_mfma_f32_16x16x32_bf16 v[68:71], v[206:209], v[234:237], v[68:71]
	v_mfma_f32_16x16x32_bf16 v[96:99], v[186:189], v[242:245], v[96:99]
	v_mfma_f32_16x16x32_bf16 v[64:67], v[206:209], v[242:245], v[64:67]
	s_barrier
	s_setprio 0
	s_add_i32 s10, s16, s63
	s_mov_b32 m0, s10
	ds_read_b128 v[214:217], v199 offset:49152
	ds_read_b128 v[218:221], v199 offset:50176
	ds_read_b128 v[222:225], v199 offset:51200
	ds_read_b128 v[226:229], v199 offset:52224
	global_load_lds_dwordx4 v154, s[98:99]
	s_add_i32 m0, s10, 0x2000
	s_add_u32 s8, s8, 0x80080
	s_addc_u32 s9, s9, 0
	s_add_i32 s10, s17, s63
	global_load_lds_dwordx4 v158, s[98:99]
	s_mov_b32 m0, s10
	ds_read_b128 v[242:245], v199 offset:56320
	global_load_lds_dwordx4 v154, s[8:9]
	s_add_i32 m0, s10, 0x2000
	ds_read_b128 v[238:241], v199 offset:55296
	global_load_lds_dwordx4 v158, s[8:9]
	s_mov_b32 m0, s82
	ds_read_b128 v[234:237], v199 offset:54272
	global_load_lds_dwordx4 v152, s[100:101]
	s_mov_b32 m0, s83
	ds_read_b128 v[230:233], v199 offset:53248
	global_load_lds_dwordx4 v156, s[100:101]
	s_waitcnt vmcnt(8)
	s_waitcnt lgkmcnt(0)
	s_setprio 1
	s_barrier
	v_mfma_f32_16x16x32_bf16 v[48:51], v[148:151], v[214:217], v[48:51]
	v_mfma_f32_16x16x32_bf16 v[16:19], v[174:177], v[214:217], v[16:19]
	v_mfma_f32_16x16x32_bf16 v[52:55], v[148:151], v[222:225], v[52:55]
	v_mfma_f32_16x16x32_bf16 v[24:27], v[174:177], v[222:225], v[24:27]
	v_mfma_f32_16x16x32_bf16 v[60:63], v[148:151], v[230:233], v[60:63]
	v_mfma_f32_16x16x32_bf16 v[28:31], v[174:177], v[230:233], v[28:31]
	v_mfma_f32_16x16x32_bf16 v[56:59], v[148:151], v[238:241], v[56:59]
	v_mfma_f32_16x16x32_bf16 v[20:23], v[174:177], v[238:241], v[20:23]
	v_mfma_f32_16x16x32_bf16 v[48:51], v[170:173], v[218:221], v[48:51]
	v_mfma_f32_16x16x32_bf16 v[16:19], v[178:181], v[218:221], v[16:19]
	v_mfma_f32_16x16x32_bf16 v[52:55], v[170:173], v[226:229], v[52:55]
	v_mfma_f32_16x16x32_bf16 v[24:27], v[178:181], v[226:229], v[24:27]
	v_mfma_f32_16x16x32_bf16 v[60:63], v[170:173], v[234:237], v[60:63]
	v_mfma_f32_16x16x32_bf16 v[28:31], v[178:181], v[234:237], v[28:31]
	v_mfma_f32_16x16x32_bf16 v[56:59], v[170:173], v[242:245], v[56:59]
	v_mfma_f32_16x16x32_bf16 v[20:23], v[178:181], v[242:245], v[20:23]
	s_setprio 0
	s_setprio 1
	v_mfma_f32_16x16x32_bf16 v[44:47], v[182:185], v[214:217], v[44:47]
	v_mfma_f32_16x16x32_bf16 v[12:15], v[202:205], v[214:217], v[12:15]
	v_mfma_f32_16x16x32_bf16 v[40:43], v[182:185], v[222:225], v[40:43]
	v_mfma_f32_16x16x32_bf16 v[8:11], v[202:205], v[222:225], v[8:11]
	v_mfma_f32_16x16x32_bf16 v[36:39], v[182:185], v[230:233], v[36:39]
	v_mfma_f32_16x16x32_bf16 v[4:7], v[202:205], v[230:233], v[4:7]
	v_mfma_f32_16x16x32_bf16 v[32:35], v[182:185], v[238:241], v[32:35]
	v_mfma_f32_16x16x32_bf16 v[0:3], v[202:205], v[238:241], v[0:3]
	v_mfma_f32_16x16x32_bf16 v[44:47], v[186:189], v[218:221], v[44:47]
	v_mfma_f32_16x16x32_bf16 v[12:15], v[206:209], v[218:221], v[12:15]
	v_mfma_f32_16x16x32_bf16 v[40:43], v[186:189], v[226:229], v[40:43]
	v_mfma_f32_16x16x32_bf16 v[8:11], v[206:209], v[226:229], v[8:11]
	v_mfma_f32_16x16x32_bf16 v[36:39], v[186:189], v[234:237], v[36:39]
	v_mfma_f32_16x16x32_bf16 v[4:7], v[206:209], v[234:237], v[4:7]
	v_mfma_f32_16x16x32_bf16 v[32:35], v[186:189], v[242:245], v[32:35]
	v_mfma_f32_16x16x32_bf16 v[0:3], v[206:209], v[242:245], v[0:3]
	s_barrier
	s_setprio 0
	s_add_i32 s15, s15, 2
	s_add_u32 s6, s6, 0x100
	s_addc_u32 s7, s7, 0
	s_add_u32 s12, s12, 0x100
	s_addc_u32 s13, s13, 0
	s_cmp_gt_u32 s15, 29
	s_cbranch_scc0 .LBB0_636
	s_and_b64 vcc, exec, s[42:43]
	s_cbranch_vccz .LBB0_639
	s_barrier

.LBB0_875:
	s_mov_b32 s1, -2
	s_mov_b64 s[4:5], s[22:23]
	ds_read_b128 v[128:131], v188
	ds_read_b128 v[132:135], v188 offset:1024
	ds_read_b128 v[136:139], v188 offset:2048
	ds_read_b128 v[140:143], v188 offset:3072
	ds_read_b128 v[144:147], v189
	ds_read_b128 v[148:151], v189 offset:1024
	ds_read_b128 v[166:169], v189 offset:2048
	ds_read_b128 v[170:173], v189 offset:3072
	s_add_u32 s40, s38, 0x100
	s_addc_u32 s41, s39, 0
	s_cmpk_eq_i32 s1, 0x52
	s_cselect_b32 s45, s37, s41
	s_cselect_b32 s44, s36, s40
	s_cselect_b32 s43, s17, s5
	s_cselect_b32 s42, s16, s4
	s_add_i32 m0, s48, 0xc000
	ds_read_b128 v[174:177], v190
	ds_read_b128 v[178:181], v190 offset:1024
	ds_read_b128 v[194:197], v190 offset:2048
	ds_read_b128 v[198:201], v190 offset:3072
	ds_read_b128 v[202:205], v190 offset:4096
	ds_read_b128 v[206:209], v190 offset:5120
	ds_read_b128 v[210:213], v190 offset:6144
	global_load_lds_dwordx4 v160, s[38:39]
	s_add_i32 m0, s48, 0xe000
	ds_read_b128 v[214:217], v190 offset:7168
	global_load_lds_dwordx4 v162, s[38:39]
	s_waitcnt vmcnt(8)
	s_waitcnt lgkmcnt(0)
	s_setprio 1
	s_barrier
	v_mfma_f32_16x16x32_bf16 v[124:127], v[128:131], v[174:177], 0
	v_mfma_f32_16x16x32_bf16 v[120:123], v[136:139], v[174:177], 0
	v_mfma_f32_16x16x32_bf16 v[108:111], v[128:131], v[194:197], 0
	v_mfma_f32_16x16x32_bf16 v[104:107], v[136:139], v[194:197], 0
	v_mfma_f32_16x16x32_bf16 v[92:95], v[128:131], v[202:205], 0
	v_mfma_f32_16x16x32_bf16 v[88:91], v[136:139], v[202:205], 0
	v_mfma_f32_16x16x32_bf16 v[76:79], v[128:131], v[210:213], 0
	v_mfma_f32_16x16x32_bf16 v[72:75], v[136:139], v[210:213], 0
	v_mfma_f32_16x16x32_bf16 v[124:127], v[132:135], v[178:181], v[124:127]
	v_mfma_f32_16x16x32_bf16 v[120:123], v[140:143], v[178:181], v[120:123]
	v_mfma_f32_16x16x32_bf16 v[108:111], v[132:135], v[198:201], v[108:111]
	v_mfma_f32_16x16x32_bf16 v[104:107], v[140:143], v[198:201], v[104:107]
	v_mfma_f32_16x16x32_bf16 v[92:95], v[132:135], v[206:209], v[92:95]
	v_mfma_f32_16x16x32_bf16 v[88:91], v[140:143], v[206:209], v[88:91]
	v_mfma_f32_16x16x32_bf16 v[76:79], v[132:135], v[214:217], v[76:79]
	v_mfma_f32_16x16x32_bf16 v[72:75], v[140:143], v[214:217], v[72:75]
	s_setprio 0
	s_setprio 1
	v_mfma_f32_16x16x32_bf16 v[116:119], v[144:147], v[174:177], 0
	v_mfma_f32_16x16x32_bf16 v[112:115], v[166:169], v[174:177], 0
	v_mfma_f32_16x16x32_bf16 v[100:103], v[144:147], v[194:197], 0
	v_mfma_f32_16x16x32_bf16 v[96:99], v[166:169], v[194:197], 0
	v_mfma_f32_16x16x32_bf16 v[84:87], v[144:147], v[202:205], 0
	v_mfma_f32_16x16x32_bf16 v[80:83], v[166:169], v[202:205], 0
	v_mfma_f32_16x16x32_bf16 v[68:71], v[144:147], v[210:213], 0
	v_mfma_f32_16x16x32_bf16 v[64:67], v[166:169], v[210:213], 0
	v_mfma_f32_16x16x32_bf16 v[116:119], v[148:151], v[178:181], v[116:119]
	v_mfma_f32_16x16x32_bf16 v[112:115], v[170:173], v[178:181], v[112:115]
	v_mfma_f32_16x16x32_bf16 v[100:103], v[148:151], v[198:201], v[100:103]
	v_mfma_f32_16x16x32_bf16 v[96:99], v[170:173], v[198:201], v[96:99]
	v_mfma_f32_16x16x32_bf16 v[84:87], v[148:151], v[206:209], v[84:87]
	v_mfma_f32_16x16x32_bf16 v[80:83], v[170:173], v[206:209], v[80:83]
	v_mfma_f32_16x16x32_bf16 v[68:71], v[148:151], v[214:217], v[68:71]
	v_mfma_f32_16x16x32_bf16 v[64:67], v[170:173], v[214:217], v[64:67]
	s_barrier
	s_setprio 0
	s_add_i32 s3, s70, s33
	s_add_u32 s98, s42, s24
	s_addc_u32 s99, s43, s25
	s_mov_b32 m0, s3
	ds_read_b128 v[174:177], v190 offset:16384
	ds_read_b128 v[178:181], v190 offset:17408
	ds_read_b128 v[194:197], v190 offset:18432
	ds_read_b128 v[198:201], v190 offset:19456
	ds_read_b128 v[202:205], v190 offset:20480
	global_load_lds_dwordx4 v154, s[42:43]
	s_add_i32 m0, s3, 0x2000
	s_add_u32 s38, s42, 0x158000
	s_addc_u32 s39, s43, 0
	s_add_i32 s3, s71, s33
	global_load_lds_dwordx4 v158, s[42:43]
	s_mov_b32 m0, s3
	s_add_u32 s100, s44, s24
	s_addc_u32 s101, s45, s25
	global_load_lds_dwordx4 v154, s[38:39]
	s_add_i32 m0, s3, 0x2000
	ds_read_b128 v[214:217], v190 offset:23552
	global_load_lds_dwordx4 v158, s[38:39]
	s_mov_b32 m0, s48
	ds_read_b128 v[210:213], v190 offset:22528
	global_load_lds_dwordx4 v152, s[44:45]
	s_mov_b32 m0, s49
	ds_read_b128 v[206:209], v190 offset:21504
	global_load_lds_dwordx4 v156, s[44:45]
	s_waitcnt vmcnt(8)
	s_waitcnt lgkmcnt(0)
	s_setprio 1
	s_barrier
	v_mfma_f32_16x16x32_bf16 v[60:63], v[128:131], v[174:177], 0
	v_mfma_f32_16x16x32_bf16 v[56:59], v[136:139], v[174:177], 0
	v_mfma_f32_16x16x32_bf16 v[44:47], v[128:131], v[194:197], 0
	v_mfma_f32_16x16x32_bf16 v[40:43], v[136:139], v[194:197], 0
	v_mfma_f32_16x16x32_bf16 v[28:31], v[128:131], v[202:205], 0
	v_mfma_f32_16x16x32_bf16 v[24:27], v[136:139], v[202:205], 0
	v_mfma_f32_16x16x32_bf16 v[12:15], v[128:131], v[210:213], 0
	v_mfma_f32_16x16x32_bf16 v[8:11], v[136:139], v[210:213], 0
	v_mfma_f32_16x16x32_bf16 v[60:63], v[132:135], v[178:181], v[60:63]
	v_mfma_f32_16x16x32_bf16 v[56:59], v[140:143], v[178:181], v[56:59]
	v_mfma_f32_16x16x32_bf16 v[44:47], v[132:135], v[198:201], v[44:47]
	v_mfma_f32_16x16x32_bf16 v[40:43], v[140:143], v[198:201], v[40:43]
	v_mfma_f32_16x16x32_bf16 v[28:31], v[132:135], v[206:209], v[28:31]
	v_mfma_f32_16x16x32_bf16 v[24:27], v[140:143], v[206:209], v[24:27]
	v_mfma_f32_16x16x32_bf16 v[12:15], v[132:135], v[214:217], v[12:15]
	v_mfma_f32_16x16x32_bf16 v[8:11], v[140:143], v[214:217], v[8:11]
	s_setprio 0
	s_setprio 1
	v_mfma_f32_16x16x32_bf16 v[52:55], v[144:147], v[174:177], 0
	v_mfma_f32_16x16x32_bf16 v[48:51], v[166:169], v[174:177], 0
	v_mfma_f32_16x16x32_bf16 v[36:39], v[144:147], v[194:197], 0
	v_mfma_f32_16x16x32_bf16 v[32:35], v[166:169], v[194:197], 0
	v_mfma_f32_16x16x32_bf16 v[20:23], v[144:147], v[202:205], 0
	v_mfma_f32_16x16x32_bf16 v[16:19], v[166:169], v[202:205], 0
	v_mfma_f32_16x16x32_bf16 v[4:7], v[144:147], v[210:213], 0
	v_mfma_f32_16x16x32_bf16 v[0:3], v[166:169], v[210:213], 0
	v_mfma_f32_16x16x32_bf16 v[52:55], v[148:151], v[178:181], v[52:55]
	v_mfma_f32_16x16x32_bf16 v[48:51], v[170:173], v[178:181], v[48:51]
	v_mfma_f32_16x16x32_bf16 v[36:39], v[148:151], v[198:201], v[36:39]
	v_mfma_f32_16x16x32_bf16 v[32:35], v[170:173], v[198:201], v[32:35]
	v_mfma_f32_16x16x32_bf16 v[20:23], v[148:151], v[206:209], v[20:23]
	v_mfma_f32_16x16x32_bf16 v[16:19], v[170:173], v[206:209], v[16:19]
	v_mfma_f32_16x16x32_bf16 v[4:7], v[148:151], v[214:217], v[4:7]
	v_mfma_f32_16x16x32_bf16 v[0:3], v[170:173], v[214:217], v[0:3]
	s_barrier
	s_setprio 0
	s_add_i32 s3, 0, 0x18000
	s_add_i32 s73, 0, 0x1c000
	v_add_u32_e32 v140, s3, v187
	v_add_u32_e32 v170, s73, v187
	ds_read_b128 v[128:131], v140
	ds_read_b128 v[132:135], v140 offset:1024
	ds_read_b128 v[136:139], v140 offset:2048
	ds_read_b128 v[140:143], v140 offset:3072
	ds_read_b128 v[144:147], v170
	ds_read_b128 v[148:151], v170 offset:1024
	ds_read_b128 v[166:169], v170 offset:2048
	ds_read_b128 v[170:173], v170 offset:3072
	s_add_u32 s38, s44, 0x158000
	s_addc_u32 s39, s45, 0
	s_mov_b32 m0, s51
	ds_read_b128 v[174:177], v190 offset:32768
	ds_read_b128 v[178:181], v190 offset:33792
	ds_read_b128 v[194:197], v190 offset:34816
	ds_read_b128 v[198:201], v190 offset:35840
	ds_read_b128 v[202:205], v190 offset:36864
	ds_read_b128 v[206:209], v190 offset:37888
	ds_read_b128 v[210:213], v190 offset:38912
	global_load_lds_dwordx4 v152, s[38:39]
	s_mov_b32 m0, s52
	ds_read_b128 v[214:217], v190 offset:39936
	global_load_lds_dwordx4 v156, s[38:39]
	s_waitcnt vmcnt(8)
	s_waitcnt lgkmcnt(0)
	s_setprio 1
	s_barrier
	v_mfma_f32_16x16x32_bf16 v[124:127], v[128:131], v[174:177], v[124:127]
	v_mfma_f32_16x16x32_bf16 v[120:123], v[136:139], v[174:177], v[120:123]
	v_mfma_f32_16x16x32_bf16 v[108:111], v[128:131], v[194:197], v[108:111]
	v_mfma_f32_16x16x32_bf16 v[104:107], v[136:139], v[194:197], v[104:107]
	v_mfma_f32_16x16x32_bf16 v[92:95], v[128:131], v[202:205], v[92:95]
	v_mfma_f32_16x16x32_bf16 v[88:91], v[136:139], v[202:205], v[88:91]
	v_mfma_f32_16x16x32_bf16 v[76:79], v[128:131], v[210:213], v[76:79]
	v_mfma_f32_16x16x32_bf16 v[72:75], v[136:139], v[210:213], v[72:75]
	v_mfma_f32_16x16x32_bf16 v[124:127], v[132:135], v[178:181], v[124:127]
	v_mfma_f32_16x16x32_bf16 v[120:123], v[140:143], v[178:181], v[120:123]
	v_mfma_f32_16x16x32_bf16 v[108:111], v[132:135], v[198:201], v[108:111]
	v_mfma_f32_16x16x32_bf16 v[104:107], v[140:143], v[198:201], v[104:107]
	v_mfma_f32_16x16x32_bf16 v[92:95], v[132:135], v[206:209], v[92:95]
	v_mfma_f32_16x16x32_bf16 v[88:91], v[140:143], v[206:209], v[88:91]
	v_mfma_f32_16x16x32_bf16 v[76:79], v[132:135], v[214:217], v[76:79]
	v_mfma_f32_16x16x32_bf16 v[72:75], v[140:143], v[214:217], v[72:75]
	s_setprio 0
	s_setprio 1
	v_mfma_f32_16x16x32_bf16 v[116:119], v[144:147], v[174:177], v[116:119]
	v_mfma_f32_16x16x32_bf16 v[112:115], v[166:169], v[174:177], v[112:115]
	v_mfma_f32_16x16x32_bf16 v[100:103], v[144:147], v[194:197], v[100:103]
	v_mfma_f32_16x16x32_bf16 v[96:99], v[166:169], v[194:197], v[96:99]
	v_mfma_f32_16x16x32_bf16 v[84:87], v[144:147], v[202:205], v[84:87]
	v_mfma_f32_16x16x32_bf16 v[80:83], v[166:169], v[202:205], v[80:83]
	v_mfma_f32_16x16x32_bf16 v[68:71], v[144:147], v[210:213], v[68:71]
	v_mfma_f32_16x16x32_bf16 v[64:67], v[166:169], v[210:213], v[64:67]
	v_mfma_f32_16x16x32_bf16 v[116:119], v[148:151], v[178:181], v[116:119]
	v_mfma_f32_16x16x32_bf16 v[112:115], v[170:173], v[178:181], v[112:115]
	v_mfma_f32_16x16x32_bf16 v[100:103], v[148:151], v[198:201], v[100:103]
	v_mfma_f32_16x16x32_bf16 v[96:99], v[170:173], v[198:201], v[96:99]
	v_mfma_f32_16x16x32_bf16 v[84:87], v[148:151], v[206:209], v[84:87]
	v_mfma_f32_16x16x32_bf16 v[80:83], v[170:173], v[206:209], v[80:83]
	v_mfma_f32_16x16x32_bf16 v[68:71], v[148:151], v[214:217], v[68:71]
	v_mfma_f32_16x16x32_bf16 v[64:67], v[170:173], v[214:217], v[64:67]
	s_barrier
	s_setprio 0
	s_add_i32 s3, s3, s33
	s_mov_b32 m0, s3
	ds_read_b128 v[174:177], v190 offset:49152
	ds_read_b128 v[178:181], v190 offset:50176
	ds_read_b128 v[194:197], v190 offset:51200
	ds_read_b128 v[198:201], v190 offset:52224
	global_load_lds_dwordx4 v154, s[98:99]
	s_add_i32 m0, s3, 0x2000
	s_add_u32 s38, s42, 0x158080
	s_addc_u32 s39, s43, 0
	s_add_i32 s3, s73, s33
	global_load_lds_dwordx4 v158, s[98:99]
	s_mov_b32 m0, s3
	ds_read_b128 v[214:217], v190 offset:56320
	global_load_lds_dwordx4 v154, s[38:39]
	s_add_i32 m0, s3, 0x2000
	ds_read_b128 v[210:213], v190 offset:55296
	global_load_lds_dwordx4 v158, s[38:39]
	s_mov_b32 m0, s56
	ds_read_b128 v[206:209], v190 offset:54272
	global_load_lds_dwordx4 v152, s[100:101]
	s_mov_b32 m0, s57
	ds_read_b128 v[202:205], v190 offset:53248
	global_load_lds_dwordx4 v156, s[100:101]
	s_waitcnt vmcnt(8)
	s_waitcnt lgkmcnt(0)
	s_setprio 1
	s_barrier
	v_mfma_f32_16x16x32_bf16 v[60:63], v[128:131], v[174:177], v[60:63]
	v_mfma_f32_16x16x32_bf16 v[56:59], v[136:139], v[174:177], v[56:59]
	v_mfma_f32_16x16x32_bf16 v[44:47], v[128:131], v[194:197], v[44:47]
	v_mfma_f32_16x16x32_bf16 v[40:43], v[136:139], v[194:197], v[40:43]
	v_mfma_f32_16x16x32_bf16 v[28:31], v[128:131], v[202:205], v[28:31]
	v_mfma_f32_16x16x32_bf16 v[24:27], v[136:139], v[202:205], v[24:27]
	v_mfma_f32_16x16x32_bf16 v[12:15], v[128:131], v[210:213], v[12:15]
	v_mfma_f32_16x16x32_bf16 v[8:11], v[136:139], v[210:213], v[8:11]
	v_mfma_f32_16x16x32_bf16 v[60:63], v[132:135], v[178:181], v[60:63]
	v_mfma_f32_16x16x32_bf16 v[56:59], v[140:143], v[178:181], v[56:59]
	v_mfma_f32_16x16x32_bf16 v[44:47], v[132:135], v[198:201], v[44:47]
	v_mfma_f32_16x16x32_bf16 v[40:43], v[140:143], v[198:201], v[40:43]
	v_mfma_f32_16x16x32_bf16 v[28:31], v[132:135], v[206:209], v[28:31]
	v_mfma_f32_16x16x32_bf16 v[24:27], v[140:143], v[206:209], v[24:27]
	v_mfma_f32_16x16x32_bf16 v[12:15], v[132:135], v[214:217], v[12:15]
	v_mfma_f32_16x16x32_bf16 v[8:11], v[140:143], v[214:217], v[8:11]
	s_setprio 0
	s_setprio 1
	v_mfma_f32_16x16x32_bf16 v[52:55], v[144:147], v[174:177], v[52:55]
	v_mfma_f32_16x16x32_bf16 v[48:51], v[166:169], v[174:177], v[48:51]
	v_mfma_f32_16x16x32_bf16 v[36:39], v[144:147], v[194:197], v[36:39]
	v_mfma_f32_16x16x32_bf16 v[32:35], v[166:169], v[194:197], v[32:35]
	v_mfma_f32_16x16x32_bf16 v[20:23], v[144:147], v[202:205], v[20:23]
	v_mfma_f32_16x16x32_bf16 v[16:19], v[166:169], v[202:205], v[16:19]
	v_mfma_f32_16x16x32_bf16 v[4:7], v[144:147], v[210:213], v[4:7]
	v_mfma_f32_16x16x32_bf16 v[0:3], v[166:169], v[210:213], v[0:3]
	v_mfma_f32_16x16x32_bf16 v[52:55], v[148:151], v[178:181], v[52:55]
	v_mfma_f32_16x16x32_bf16 v[48:51], v[170:173], v[178:181], v[48:51]
	v_mfma_f32_16x16x32_bf16 v[36:39], v[148:151], v[198:201], v[36:39]
	v_mfma_f32_16x16x32_bf16 v[32:35], v[170:173], v[198:201], v[32:35]
	v_mfma_f32_16x16x32_bf16 v[20:23], v[148:151], v[206:209], v[20:23]
	v_mfma_f32_16x16x32_bf16 v[16:19], v[170:173], v[206:209], v[16:19]
	v_mfma_f32_16x16x32_bf16 v[4:7], v[148:151], v[214:217], v[4:7]
	v_mfma_f32_16x16x32_bf16 v[0:3], v[170:173], v[214:217], v[0:3]
	s_barrier
	s_setprio 0
	s_add_i32 s1, s1, 2
	s_add_u32 s4, s4, 0x100
	s_addc_u32 s5, s5, 0
	s_cmpk_gt_u32 s1, 0x53
	s_mov_b64 s[38:39], s[40:41]
.LBB0_876:
	ds_read_b128 v[128:131], v188
	ds_read_b128 v[132:135], v188 offset:1024
	ds_read_b128 v[136:139], v188 offset:2048
	ds_read_b128 v[140:143], v188 offset:3072
	ds_read_b128 v[144:147], v189
	ds_read_b128 v[148:151], v189 offset:1024
	ds_read_b128 v[166:169], v189 offset:2048
	ds_read_b128 v[170:173], v189 offset:3072
	s_add_u32 s40, s38, 0x100
	s_addc_u32 s41, s39, 0
	s_cmpk_eq_i32 s1, 0x52
	s_cselect_b32 s45, s37, s41
	s_cselect_b32 s44, s36, s40
	s_cselect_b32 s43, s17, s5
	s_cselect_b32 s42, s16, s4
	s_add_i32 m0, s48, 0xc000
	ds_read_b128 v[174:177], v190
	ds_read_b128 v[178:181], v190 offset:1024
	ds_read_b128 v[194:197], v190 offset:2048
	ds_read_b128 v[198:201], v190 offset:3072
	ds_read_b128 v[202:205], v190 offset:4096
	ds_read_b128 v[206:209], v190 offset:5120
	ds_read_b128 v[210:213], v190 offset:6144
	global_load_lds_dwordx4 v160, s[38:39]
	s_add_i32 m0, s48, 0xe000
	ds_read_b128 v[214:217], v190 offset:7168
	global_load_lds_dwordx4 v162, s[38:39]
	s_waitcnt vmcnt(8)
	s_waitcnt lgkmcnt(0)
	s_setprio 1
	s_barrier
	v_mfma_f32_16x16x32_bf16 v[124:127], v[128:131], v[174:177], v[124:127]
	v_mfma_f32_16x16x32_bf16 v[120:123], v[136:139], v[174:177], v[120:123]
	v_mfma_f32_16x16x32_bf16 v[108:111], v[128:131], v[194:197], v[108:111]
	v_mfma_f32_16x16x32_bf16 v[104:107], v[136:139], v[194:197], v[104:107]
	v_mfma_f32_16x16x32_bf16 v[92:95], v[128:131], v[202:205], v[92:95]
	v_mfma_f32_16x16x32_bf16 v[88:91], v[136:139], v[202:205], v[88:91]
	v_mfma_f32_16x16x32_bf16 v[76:79], v[128:131], v[210:213], v[76:79]
	v_mfma_f32_16x16x32_bf16 v[72:75], v[136:139], v[210:213], v[72:75]
	v_mfma_f32_16x16x32_bf16 v[124:127], v[132:135], v[178:181], v[124:127]
	v_mfma_f32_16x16x32_bf16 v[120:123], v[140:143], v[178:181], v[120:123]
	v_mfma_f32_16x16x32_bf16 v[108:111], v[132:135], v[198:201], v[108:111]
	v_mfma_f32_16x16x32_bf16 v[104:107], v[140:143], v[198:201], v[104:107]
	v_mfma_f32_16x16x32_bf16 v[92:95], v[132:135], v[206:209], v[92:95]
	v_mfma_f32_16x16x32_bf16 v[88:91], v[140:143], v[206:209], v[88:91]
	v_mfma_f32_16x16x32_bf16 v[76:79], v[132:135], v[214:217], v[76:79]
	v_mfma_f32_16x16x32_bf16 v[72:75], v[140:143], v[214:217], v[72:75]
	s_setprio 0
	s_setprio 1
	v_mfma_f32_16x16x32_bf16 v[116:119], v[144:147], v[174:177], v[116:119]
	v_mfma_f32_16x16x32_bf16 v[112:115], v[166:169], v[174:177], v[112:115]
	v_mfma_f32_16x16x32_bf16 v[100:103], v[144:147], v[194:197], v[100:103]
	v_mfma_f32_16x16x32_bf16 v[96:99], v[166:169], v[194:197], v[96:99]
	v_mfma_f32_16x16x32_bf16 v[84:87], v[144:147], v[202:205], v[84:87]
	v_mfma_f32_16x16x32_bf16 v[80:83], v[166:169], v[202:205], v[80:83]
	v_mfma_f32_16x16x32_bf16 v[68:71], v[144:147], v[210:213], v[68:71]
	v_mfma_f32_16x16x32_bf16 v[64:67], v[166:169], v[210:213], v[64:67]
	v_mfma_f32_16x16x32_bf16 v[116:119], v[148:151], v[178:181], v[116:119]
	v_mfma_f32_16x16x32_bf16 v[112:115], v[170:173], v[178:181], v[112:115]
	v_mfma_f32_16x16x32_bf16 v[100:103], v[148:151], v[198:201], v[100:103]
	v_mfma_f32_16x16x32_bf16 v[96:99], v[170:173], v[198:201], v[96:99]
	v_mfma_f32_16x16x32_bf16 v[84:87], v[148:151], v[206:209], v[84:87]
	v_mfma_f32_16x16x32_bf16 v[80:83], v[170:173], v[206:209], v[80:83]
	v_mfma_f32_16x16x32_bf16 v[68:71], v[148:151], v[214:217], v[68:71]
	v_mfma_f32_16x16x32_bf16 v[64:67], v[170:173], v[214:217], v[64:67]
	s_barrier
	s_setprio 0
	s_add_i32 s3, s70, s33
	s_add_u32 s98, s42, s24
	s_addc_u32 s99, s43, s25
	s_mov_b32 m0, s3
	ds_read_b128 v[174:177], v190 offset:16384
	ds_read_b128 v[178:181], v190 offset:17408
	ds_read_b128 v[194:197], v190 offset:18432
	ds_read_b128 v[198:201], v190 offset:19456
	ds_read_b128 v[202:205], v190 offset:20480
	global_load_lds_dwordx4 v154, s[42:43]
	s_add_i32 m0, s3, 0x2000
	s_add_u32 s38, s42, 0x158000
	s_addc_u32 s39, s43, 0
	s_add_i32 s3, s71, s33
	global_load_lds_dwordx4 v158, s[42:43]
	s_mov_b32 m0, s3
	s_add_u32 s100, s44, s24
	s_addc_u32 s101, s45, s25
	global_load_lds_dwordx4 v154, s[38:39]
	s_add_i32 m0, s3, 0x2000
	ds_read_b128 v[214:217], v190 offset:23552
	global_load_lds_dwordx4 v158, s[38:39]
	s_mov_b32 m0, s48
	ds_read_b128 v[210:213], v190 offset:22528
	global_load_lds_dwordx4 v152, s[44:45]
	s_mov_b32 m0, s49
	ds_read_b128 v[206:209], v190 offset:21504
	global_load_lds_dwordx4 v156, s[44:45]
	s_waitcnt vmcnt(8)
	s_waitcnt lgkmcnt(0)
	s_setprio 1
	s_barrier
	v_mfma_f32_16x16x32_bf16 v[60:63], v[128:131], v[174:177], v[60:63]
	v_mfma_f32_16x16x32_bf16 v[56:59], v[136:139], v[174:177], v[56:59]
	v_mfma_f32_16x16x32_bf16 v[44:47], v[128:131], v[194:197], v[44:47]
	v_mfma_f32_16x16x32_bf16 v[40:43], v[136:139], v[194:197], v[40:43]
	v_mfma_f32_16x16x32_bf16 v[28:31], v[128:131], v[202:205], v[28:31]
	v_mfma_f32_16x16x32_bf16 v[24:27], v[136:139], v[202:205], v[24:27]
	v_mfma_f32_16x16x32_bf16 v[12:15], v[128:131], v[210:213], v[12:15]
	v_mfma_f32_16x16x32_bf16 v[8:11], v[136:139], v[210:213], v[8:11]
	v_mfma_f32_16x16x32_bf16 v[60:63], v[132:135], v[178:181], v[60:63]
	v_mfma_f32_16x16x32_bf16 v[56:59], v[140:143], v[178:181], v[56:59]
	v_mfma_f32_16x16x32_bf16 v[44:47], v[132:135], v[198:201], v[44:47]
	v_mfma_f32_16x16x32_bf16 v[40:43], v[140:143], v[198:201], v[40:43]
	v_mfma_f32_16x16x32_bf16 v[28:31], v[132:135], v[206:209], v[28:31]
	v_mfma_f32_16x16x32_bf16 v[24:27], v[140:143], v[206:209], v[24:27]
	v_mfma_f32_16x16x32_bf16 v[12:15], v[132:135], v[214:217], v[12:15]
	v_mfma_f32_16x16x32_bf16 v[8:11], v[140:143], v[214:217], v[8:11]
	s_setprio 0
	s_setprio 1
	v_mfma_f32_16x16x32_bf16 v[52:55], v[144:147], v[174:177], v[52:55]
	v_mfma_f32_16x16x32_bf16 v[48:51], v[166:169], v[174:177], v[48:51]
	v_mfma_f32_16x16x32_bf16 v[36:39], v[144:147], v[194:197], v[36:39]
	v_mfma_f32_16x16x32_bf16 v[32:35], v[166:169], v[194:197], v[32:35]
	v_mfma_f32_16x16x32_bf16 v[20:23], v[144:147], v[202:205], v[20:23]
	v_mfma_f32_16x16x32_bf16 v[16:19], v[166:169], v[202:205], v[16:19]
	v_mfma_f32_16x16x32_bf16 v[4:7], v[144:147], v[210:213], v[4:7]
	v_mfma_f32_16x16x32_bf16 v[0:3], v[166:169], v[210:213], v[0:3]
	v_mfma_f32_16x16x32_bf16 v[52:55], v[148:151], v[178:181], v[52:55]
	v_mfma_f32_16x16x32_bf16 v[48:51], v[170:173], v[178:181], v[48:51]
	v_mfma_f32_16x16x32_bf16 v[36:39], v[148:151], v[198:201], v[36:39]
	v_mfma_f32_16x16x32_bf16 v[32:35], v[170:173], v[198:201], v[32:35]
	v_mfma_f32_16x16x32_bf16 v[20:23], v[148:151], v[206:209], v[20:23]
	v_mfma_f32_16x16x32_bf16 v[16:19], v[170:173], v[206:209], v[16:19]
	v_mfma_f32_16x16x32_bf16 v[4:7], v[148:151], v[214:217], v[4:7]
	v_mfma_f32_16x16x32_bf16 v[0:3], v[170:173], v[214:217], v[0:3]
	s_barrier
	s_setprio 0
	s_add_i32 s3, 0, 0x18000
	s_add_i32 s73, 0, 0x1c000
	v_add_u32_e32 v140, s3, v187
	v_add_u32_e32 v170, s73, v187
	ds_read_b128 v[128:131], v140
	ds_read_b128 v[132:135], v140 offset:1024
	ds_read_b128 v[136:139], v140 offset:2048
	ds_read_b128 v[140:143], v140 offset:3072
	ds_read_b128 v[144:147], v170
	ds_read_b128 v[148:151], v170 offset:1024
	ds_read_b128 v[166:169], v170 offset:2048
	ds_read_b128 v[170:173], v170 offset:3072
	s_add_u32 s38, s44, 0x158000
	s_addc_u32 s39, s45, 0
	s_mov_b32 m0, s51
	ds_read_b128 v[174:177], v190 offset:32768
	ds_read_b128 v[178:181], v190 offset:33792
	ds_read_b128 v[194:197], v190 offset:34816
	ds_read_b128 v[198:201], v190 offset:35840
	ds_read_b128 v[202:205], v190 offset:36864
	ds_read_b128 v[206:209], v190 offset:37888
	ds_read_b128 v[210:213], v190 offset:38912
	global_load_lds_dwordx4 v152, s[38:39]
	s_mov_b32 m0, s52
	ds_read_b128 v[214:217], v190 offset:39936
	global_load_lds_dwordx4 v156, s[38:39]
	s_waitcnt vmcnt(8)
	s_waitcnt lgkmcnt(0)
	s_setprio 1
	s_barrier
	v_mfma_f32_16x16x32_bf16 v[124:127], v[128:131], v[174:177], v[124:127]
	v_mfma_f32_16x16x32_bf16 v[120:123], v[136:139], v[174:177], v[120:123]
	v_mfma_f32_16x16x32_bf16 v[108:111], v[128:131], v[194:197], v[108:111]
	v_mfma_f32_16x16x32_bf16 v[104:107], v[136:139], v[194:197], v[104:107]
	v_mfma_f32_16x16x32_bf16 v[92:95], v[128:131], v[202:205], v[92:95]
	v_mfma_f32_16x16x32_bf16 v[88:91], v[136:139], v[202:205], v[88:91]
	v_mfma_f32_16x16x32_bf16 v[76:79], v[128:131], v[210:213], v[76:79]
	v_mfma_f32_16x16x32_bf16 v[72:75], v[136:139], v[210:213], v[72:75]
	v_mfma_f32_16x16x32_bf16 v[124:127], v[132:135], v[178:181], v[124:127]
	v_mfma_f32_16x16x32_bf16 v[120:123], v[140:143], v[178:181], v[120:123]
	v_mfma_f32_16x16x32_bf16 v[108:111], v[132:135], v[198:201], v[108:111]
	v_mfma_f32_16x16x32_bf16 v[104:107], v[140:143], v[198:201], v[104:107]
	v_mfma_f32_16x16x32_bf16 v[92:95], v[132:135], v[206:209], v[92:95]
	v_mfma_f32_16x16x32_bf16 v[88:91], v[140:143], v[206:209], v[88:91]
	v_mfma_f32_16x16x32_bf16 v[76:79], v[132:135], v[214:217], v[76:79]
	v_mfma_f32_16x16x32_bf16 v[72:75], v[140:143], v[214:217], v[72:75]
	s_setprio 0
	s_setprio 1
	v_mfma_f32_16x16x32_bf16 v[116:119], v[144:147], v[174:177], v[116:119]
	v_mfma_f32_16x16x32_bf16 v[112:115], v[166:169], v[174:177], v[112:115]
	v_mfma_f32_16x16x32_bf16 v[100:103], v[144:147], v[194:197], v[100:103]
	v_mfma_f32_16x16x32_bf16 v[96:99], v[166:169], v[194:197], v[96:99]
	v_mfma_f32_16x16x32_bf16 v[84:87], v[144:147], v[202:205], v[84:87]
	v_mfma_f32_16x16x32_bf16 v[80:83], v[166:169], v[202:205], v[80:83]
	v_mfma_f32_16x16x32_bf16 v[68:71], v[144:147], v[210:213], v[68:71]
	v_mfma_f32_16x16x32_bf16 v[64:67], v[166:169], v[210:213], v[64:67]
	v_mfma_f32_16x16x32_bf16 v[116:119], v[148:151], v[178:181], v[116:119]
	v_mfma_f32_16x16x32_bf16 v[112:115], v[170:173], v[178:181], v[112:115]
	v_mfma_f32_16x16x32_bf16 v[100:103], v[148:151], v[198:201], v[100:103]
	v_mfma_f32_16x16x32_bf16 v[96:99], v[170:173], v[198:201], v[96:99]
	v_mfma_f32_16x16x32_bf16 v[84:87], v[148:151], v[206:209], v[84:87]
	v_mfma_f32_16x16x32_bf16 v[80:83], v[170:173], v[206:209], v[80:83]
	v_mfma_f32_16x16x32_bf16 v[68:71], v[148:151], v[214:217], v[68:71]
	v_mfma_f32_16x16x32_bf16 v[64:67], v[170:173], v[214:217], v[64:67]
	s_barrier
	s_setprio 0
	s_add_i32 s3, s3, s33
	s_mov_b32 m0, s3
	ds_read_b128 v[174:177], v190 offset:49152
	ds_read_b128 v[178:181], v190 offset:50176
	ds_read_b128 v[194:197], v190 offset:51200
	ds_read_b128 v[198:201], v190 offset:52224
	global_load_lds_dwordx4 v154, s[98:99]
	s_add_i32 m0, s3, 0x2000
	s_add_u32 s38, s42, 0x158080
	s_addc_u32 s39, s43, 0
	s_add_i32 s3, s73, s33
	global_load_lds_dwordx4 v158, s[98:99]
	s_mov_b32 m0, s3
	ds_read_b128 v[214:217], v190 offset:56320
	global_load_lds_dwordx4 v154, s[38:39]
	s_add_i32 m0, s3, 0x2000
	ds_read_b128 v[210:213], v190 offset:55296
	global_load_lds_dwordx4 v158, s[38:39]
	s_mov_b32 m0, s56
	ds_read_b128 v[206:209], v190 offset:54272
	global_load_lds_dwordx4 v152, s[100:101]
	s_mov_b32 m0, s57
	ds_read_b128 v[202:205], v190 offset:53248
	global_load_lds_dwordx4 v156, s[100:101]
	s_waitcnt vmcnt(8)
	s_waitcnt lgkmcnt(0)
	s_setprio 1
	s_barrier
	v_mfma_f32_16x16x32_bf16 v[60:63], v[128:131], v[174:177], v[60:63]
	v_mfma_f32_16x16x32_bf16 v[56:59], v[136:139], v[174:177], v[56:59]
	v_mfma_f32_16x16x32_bf16 v[44:47], v[128:131], v[194:197], v[44:47]
	v_mfma_f32_16x16x32_bf16 v[40:43], v[136:139], v[194:197], v[40:43]
	v_mfma_f32_16x16x32_bf16 v[28:31], v[128:131], v[202:205], v[28:31]
	v_mfma_f32_16x16x32_bf16 v[24:27], v[136:139], v[202:205], v[24:27]
	v_mfma_f32_16x16x32_bf16 v[12:15], v[128:131], v[210:213], v[12:15]
	v_mfma_f32_16x16x32_bf16 v[8:11], v[136:139], v[210:213], v[8:11]
	v_mfma_f32_16x16x32_bf16 v[60:63], v[132:135], v[178:181], v[60:63]
	v_mfma_f32_16x16x32_bf16 v[56:59], v[140:143], v[178:181], v[56:59]
	v_mfma_f32_16x16x32_bf16 v[44:47], v[132:135], v[198:201], v[44:47]
	v_mfma_f32_16x16x32_bf16 v[40:43], v[140:143], v[198:201], v[40:43]
	v_mfma_f32_16x16x32_bf16 v[28:31], v[132:135], v[206:209], v[28:31]
	v_mfma_f32_16x16x32_bf16 v[24:27], v[140:143], v[206:209], v[24:27]
	v_mfma_f32_16x16x32_bf16 v[12:15], v[132:135], v[214:217], v[12:15]
	v_mfma_f32_16x16x32_bf16 v[8:11], v[140:143], v[214:217], v[8:11]
	s_setprio 0
	s_setprio 1
	v_mfma_f32_16x16x32_bf16 v[52:55], v[144:147], v[174:177], v[52:55]
	v_mfma_f32_16x16x32_bf16 v[48:51], v[166:169], v[174:177], v[48:51]
	v_mfma_f32_16x16x32_bf16 v[36:39], v[144:147], v[194:197], v[36:39]
	v_mfma_f32_16x16x32_bf16 v[32:35], v[166:169], v[194:197], v[32:35]
	v_mfma_f32_16x16x32_bf16 v[20:23], v[144:147], v[202:205], v[20:23]
	v_mfma_f32_16x16x32_bf16 v[16:19], v[166:169], v[202:205], v[16:19]
	v_mfma_f32_16x16x32_bf16 v[4:7], v[144:147], v[210:213], v[4:7]
	v_mfma_f32_16x16x32_bf16 v[0:3], v[166:169], v[210:213], v[0:3]
	v_mfma_f32_16x16x32_bf16 v[52:55], v[148:151], v[178:181], v[52:55]
	v_mfma_f32_16x16x32_bf16 v[48:51], v[170:173], v[178:181], v[48:51]
	v_mfma_f32_16x16x32_bf16 v[36:39], v[148:151], v[198:201], v[36:39]
	v_mfma_f32_16x16x32_bf16 v[32:35], v[170:173], v[198:201], v[32:35]
	v_mfma_f32_16x16x32_bf16 v[20:23], v[148:151], v[206:209], v[20:23]
	v_mfma_f32_16x16x32_bf16 v[16:19], v[170:173], v[206:209], v[16:19]
	v_mfma_f32_16x16x32_bf16 v[4:7], v[148:151], v[214:217], v[4:7]
	v_mfma_f32_16x16x32_bf16 v[0:3], v[170:173], v[214:217], v[0:3]
	s_barrier
	s_setprio 0
	s_add_i32 s1, s1, 2
	s_add_u32 s4, s4, 0x100
	s_addc_u32 s5, s5, 0
	s_cmpk_gt_u32 s1, 0x53
	s_mov_b64 s[38:39], s[40:41]
	s_cbranch_scc0 .LBB0_876
	s_and_b64 vcc, exec, s[26:27]
	s_cbranch_vccz .LBB0_879
	s_barrier
